# staging writes/re-issue moved to MFMA groups 4-11 (was 1-8)
# speedup vs baseline: 1.0108x; 1.0011x over previous
; template <int MI, int NJ> ...
;     ...
;   for (int kt = 0; kt < nk; ++kt) {
;     const int buf = kt & 1;
;     {
;       G8STORE(buf ^ 1);
;       const u16* ga_ = (kt + 2 < nk) ? Ag + (kt + 2) * 64 : Ag + nAoff;
;       const u16* gb_ = (kt + 2 < nk) ? Bg + (kt + 2) * 64 : Bg + nBoff;
;       G8LOADP(ga_, gb_);
;     }
;     __builtin_amdgcn_sched_barrier(0);
;     __builtin_amdgcn_s_setprio(1);
;     const u16* a = ra_ + buf * AROWS * 64;
;     const u16* b = rb_ + buf * BROWS * 64;
; #pragma unroll
;     for (int ks = 0; ks < 2; ++ks) {
;       const u16* a_ = ks ? a + dsw : a;
;       const u16* b_ = ks ? b + dsw : b;
;       bf16x8 bfr[NJ];
; #pragma unroll
;       for (int j = 0; j < NJ; ++j) bfr[j] = *(const bf16x8*)(b_ + j * 16 * 64);
; #pragma unroll
;       for (int ih = 0; ih < MI / 4; ++ih) {
;         bf16x8 af[4];
; #pragma unroll
;         for (int i = 0; i < 4; ++i) af[i] = *(const bf16x8*)(a_ + (ih * 4 + i) * 16 * 64);
; #pragma unroll
;         for (int i = 0; i < 4; ++i)
; #pragma unroll
;           for (int j = 0; j < NJ; ++j) acc[ih * 4 + i][j] = mfma16(af[i], bfr[j], acc[ih * 4 + i][j]);
;       }
;     }
;     __builtin_amdgcn_s_setprio(0);
;     __builtin_amdgcn_sched_barrier(0);
;     __syncthreads();
;   }
.LBB0_470:
	s_setprio 1
	s_waitcnt lgkmcnt(6)
	v_mfma_f32_16x16x32_bf16 v[158:161], v[166:169], v[162:165], v[158:161]
	s_waitcnt lgkmcnt(5)
	v_mfma_f32_16x16x32_bf16 v[154:157], v[170:173], v[162:165], v[154:157]
	s_waitcnt lgkmcnt(4)
	v_mfma_f32_16x16x32_bf16 v[150:153], v[192:195], v[162:165], v[150:153]
	s_waitcnt lgkmcnt(3)
	v_mfma_f32_16x16x32_bf16 v[146:149], v[196:199], v[162:165], v[146:149]
	ds_read_b128 v[162:165], v0 offset:8192
	s_waitcnt lgkmcnt(3)
	v_mfma_f32_16x16x32_bf16 v[142:145], v[166:169], v[204:207], v[142:145]
	v_mfma_f32_16x16x32_bf16 v[138:141], v[170:173], v[204:207], v[138:141]
	v_mfma_f32_16x16x32_bf16 v[134:137], v[192:195], v[204:207], v[134:137]
	v_mfma_f32_16x16x32_bf16 v[130:133], v[196:199], v[204:207], v[130:133]
	ds_read_b128 v[204:207], v0 offset:10240
	s_waitcnt lgkmcnt(3)
	v_mfma_f32_16x16x32_bf16 v[126:129], v[166:169], v[208:211], v[126:129]
	v_mfma_f32_16x16x32_bf16 v[122:125], v[170:173], v[208:211], v[122:125]
	v_mfma_f32_16x16x32_bf16 v[118:121], v[192:195], v[208:211], v[118:121]
	v_mfma_f32_16x16x32_bf16 v[114:117], v[196:199], v[208:211], v[114:117]
	ds_read_b128 v[208:211], v0 offset:12288
	ds_read_b128 v[212:215], v191
	ds_read_b128 v[216:219], v191 offset:2048
	s_waitcnt lgkmcnt(5)
	v_mfma_f32_16x16x32_bf16 v[110:113], v[166:169], v[238:241], v[110:113]
	v_mfma_f32_16x16x32_bf16 v[106:109], v[170:173], v[238:241], v[106:109]
	v_mfma_f32_16x16x32_bf16 v[102:105], v[192:195], v[238:241], v[102:105]
	v_mfma_f32_16x16x32_bf16 v[98:101], v[196:199], v[238:241], v[98:101]
	ds_read_b128 v[238:241], v0 offset:14336
	ds_read_b128 v[220:223], v191 offset:4096
	ds_read_b128 v[224:227], v191 offset:6144
	s_waitcnt lgkmcnt(7)
	v_mfma_f32_16x16x32_bf16 v[94:97], v[166:169], v[162:165], v[94:97]
	v_mfma_f32_16x16x32_bf16 v[90:93], v[170:173], v[162:165], v[90:93]
	v_mfma_f32_16x16x32_bf16 v[86:89], v[192:195], v[162:165], v[86:89]
	v_mfma_f32_16x16x32_bf16 v[82:85], v[196:199], v[162:165], v[82:85]
	v_add_u32_e32 v0, v0, v190
	ds_read_b128 v[162:165], v0
	s_waitcnt vmcnt(7)
	ds_write_b128 v228, v[10:13]
	global_load_dwordx4 v[10:13], v234, s[52:53]
	s_waitcnt lgkmcnt(8)
	v_mfma_f32_16x16x32_bf16 v[78:81], v[166:169], v[204:207], v[78:81]
	v_mfma_f32_16x16x32_bf16 v[74:77], v[170:173], v[204:207], v[74:77]
	v_mfma_f32_16x16x32_bf16 v[70:73], v[192:195], v[204:207], v[70:73]
	v_mfma_f32_16x16x32_bf16 v[66:69], v[196:199], v[204:207], v[66:69]
	ds_read_b128 v[204:207], v0 offset:2048
	s_waitcnt vmcnt(7)
	ds_write_b128 v228, v[2:5] offset:8192
	global_load_dwordx4 v[2:5], v235, s[52:53]
	s_waitcnt lgkmcnt(9)
	v_mfma_f32_16x16x32_bf16 v[62:65], v[166:169], v[208:211], v[62:65]
	v_mfma_f32_16x16x32_bf16 v[58:61], v[170:173], v[208:211], v[58:61]
	v_mfma_f32_16x16x32_bf16 v[54:57], v[192:195], v[208:211], v[54:57]
	v_mfma_f32_16x16x32_bf16 v[50:53], v[196:199], v[208:211], v[50:53]
	ds_read_b128 v[208:211], v0 offset:4096
	s_waitcnt vmcnt(7)
	ds_write_b128 v228, v[6:9] offset:16384
	global_load_dwordx4 v[6:9], v236, s[52:53]
	s_waitcnt lgkmcnt(8)
	v_mfma_f32_16x16x32_bf16 v[46:49], v[166:169], v[238:241], v[46:49]
	v_mfma_f32_16x16x32_bf16 v[42:45], v[170:173], v[238:241], v[42:45]
	v_mfma_f32_16x16x32_bf16 v[38:41], v[192:195], v[238:241], v[38:41]
	v_mfma_f32_16x16x32_bf16 v[34:37], v[196:199], v[238:241], v[34:37]
	ds_read_b128 v[238:241], v0 offset:6144
	s_waitcnt vmcnt(7)
	ds_write_b128 v228, v[18:21] offset:24576
	global_load_dwordx4 v[18:21], v237, s[52:53]
	s_waitcnt lgkmcnt(7)
	v_mfma_f32_16x16x32_bf16 v[158:161], v[212:215], v[162:165], v[158:161]
	v_mfma_f32_16x16x32_bf16 v[154:157], v[216:219], v[162:165], v[154:157]
	v_mfma_f32_16x16x32_bf16 v[150:153], v[220:223], v[162:165], v[150:153]
	v_mfma_f32_16x16x32_bf16 v[146:149], v[224:227], v[162:165], v[146:149]
	ds_read_b128 v[162:165], v0 offset:8192
	s_waitcnt vmcnt(7)
	ds_write_b128 v229, v[14:17]
	global_load_dwordx4 v[14:17], v234, s[66:67]
	s_waitcnt lgkmcnt(7)
	v_mfma_f32_16x16x32_bf16 v[142:145], v[212:215], v[204:207], v[142:145]
	v_mfma_f32_16x16x32_bf16 v[138:141], v[216:219], v[204:207], v[138:141]
	v_mfma_f32_16x16x32_bf16 v[134:137], v[220:223], v[204:207], v[134:137]
	v_mfma_f32_16x16x32_bf16 v[130:133], v[224:227], v[204:207], v[130:133]
	ds_read_b128 v[204:207], v0 offset:10240
	s_waitcnt vmcnt(7)
	ds_write_b128 v229, v[22:25] offset:8192
	global_load_dwordx4 v[22:25], v235, s[66:67]
	s_waitcnt lgkmcnt(7)
	v_mfma_f32_16x16x32_bf16 v[126:129], v[212:215], v[208:211], v[126:129]
	v_mfma_f32_16x16x32_bf16 v[122:125], v[216:219], v[208:211], v[122:125]
	v_mfma_f32_16x16x32_bf16 v[118:121], v[220:223], v[208:211], v[118:121]
	v_mfma_f32_16x16x32_bf16 v[114:117], v[224:227], v[208:211], v[114:117]
	ds_read_b128 v[208:211], v0 offset:12288
	s_waitcnt vmcnt(7)
	ds_write_b128 v229, v[26:29] offset:16384
	global_load_dwordx4 v[26:29], v236, s[66:67]
	s_waitcnt lgkmcnt(7)
	v_mfma_f32_16x16x32_bf16 v[110:113], v[212:215], v[238:241], v[110:113]
	v_mfma_f32_16x16x32_bf16 v[106:109], v[216:219], v[238:241], v[106:109]
	v_mfma_f32_16x16x32_bf16 v[102:105], v[220:223], v[238:241], v[102:105]
	v_mfma_f32_16x16x32_bf16 v[98:101], v[224:227], v[238:241], v[98:101]
	ds_read_b128 v[238:241], v0 offset:14336
	s_waitcnt vmcnt(7)
	ds_write_b128 v229, v[30:33] offset:24576
	global_load_dwordx4 v[30:33], v237, s[66:67]
	s_waitcnt lgkmcnt(7)
	v_mfma_f32_16x16x32_bf16 v[94:97], v[212:215], v[162:165], v[94:97]
	v_mfma_f32_16x16x32_bf16 v[90:93], v[216:219], v[162:165], v[90:93]
	v_mfma_f32_16x16x32_bf16 v[86:89], v[220:223], v[162:165], v[86:89]
	v_mfma_f32_16x16x32_bf16 v[82:85], v[224:227], v[162:165], v[82:85]
	s_waitcnt lgkmcnt(0)
	s_setprio 0
	s_barrier
; template <int MI, int NJ> ...
;     ...
;   for (int kt = 0; kt < nk; ++kt) {
;     const int buf = kt & 1;
;     {
;       G8STORE(buf ^ 1);
;       const u16* ga_ = (kt + 2 < nk) ? Ag + (kt + 2) * 64 : Ag + nAoff;
;       const u16* gb_ = (kt + 2 < nk) ? Bg + (kt + 2) * 64 : Bg + nBoff;
;       G8LOADP(ga_, gb_);
;     }
;     __builtin_amdgcn_sched_barrier(0);
;     __builtin_amdgcn_s_setprio(1);
;     const u16* a = ra_ + buf * AROWS * 64;
;     const u16* b = rb_ + buf * BROWS * 64;
; #pragma unroll
;     for (int ks = 0; ks < 2; ++ks) {
;       const u16* a_ = ks ? a + dsw : a;
;       const u16* b_ = ks ? b + dsw : b;
;       bf16x8 bfr[NJ];
; #pragma unroll
;       for (int j = 0; j < NJ; ++j) bfr[j] = *(const bf16x8*)(b_ + j * 16 * 64);
; #pragma unroll
;       for (int ih = 0; ih < MI / 4; ++ih) {
;         bf16x8 af[4];
; #pragma unroll
;         for (int i = 0; i < 4; ++i) af[i] = *(const bf16x8*)(a_ + (ih * 4 + i) * 16 * 64);
; #pragma unroll
;         for (int i = 0; i < 4; ++i)
; #pragma unroll
;           for (int j = 0; j < NJ; ++j) acc[ih * 4 + i][j] = mfma16(af[i], bfr[j], acc[ih * 4 + i][j]);
;       }
;     }
;     __builtin_amdgcn_s_setprio(0);
;     __builtin_amdgcn_sched_barrier(0);
;     __syncthreads();
;   }
; __device__ __forceinline__ void phase_win(const Params& p, int part, u16* smem, volatile LAS unsigned* vb_) {
;     ...
; #pragma unroll
;     for (int i = 0; i < 8; ++i)
; #pragma unroll
;       for (int j = 0; j < 4; ++j)
; #pragma unroll
;         for (int r = 0; r < 4; ++r)
;           smem[(wm * 128 + i * 16 + (lane >> 4) * 4 + r) * 264 + wn * 64 + j * 16 + (lane & 15)] = f2bf(acc[i][j][r]);
	s_add_i32 s37, s37, 1
	s_add_u32 s20, s20, 64
	s_addc_u32 s21, s21, 0
	s_addk_i32 s11, 0x4000
	s_and_b32 s38, s11, 0x4000
	s_xor_b32 s39, s38, 0x4000
	s_lshl_b32 s39, s39, 1
	v_add_u32_e32 v228, s39, v185
	v_add_u32_e32 v229, s39, v186
	s_cmp_lt_u32 s37, 14
	s_cselect_b32 s49, s21, s13
	s_cselect_b32 s48, s20, s12
	s_cselect_b32 s51, s21, s47
	s_cselect_b32 s50, s20, s46
	s_lshl_b64 s[48:49], s[48:49], 1
	s_lshl_b64 s[50:51], s[50:51], 1
	s_add_u32 s52, s62, s48
	s_addc_u32 s53, s63, s49
	s_add_u32 s66, s64, s50
	s_addc_u32 s67, s65, s51
	s_lshl_b32 s38, s38, 1
	v_add_u32_e32 v0, s38, v187
	v_add_u32_e32 v191, s38, v188
	s_setprio 1
	ds_read_b128 v[166:169], v191
	ds_read_b128 v[162:165], v0
	ds_read_b128 v[170:173], v191 offset:2048
	ds_read_b128 v[192:195], v191 offset:4096
	ds_read_b128 v[196:199], v191 offset:6144
	v_mfma_f32_16x16x32_bf16 v[78:81], v[212:215], v[204:207], v[78:81]
	v_mfma_f32_16x16x32_bf16 v[74:77], v[216:219], v[204:207], v[74:77]
	v_mfma_f32_16x16x32_bf16 v[70:73], v[220:223], v[204:207], v[70:73]
	v_mfma_f32_16x16x32_bf16 v[66:69], v[224:227], v[204:207], v[66:69]
	ds_read_b128 v[204:207], v0 offset:2048
	v_mfma_f32_16x16x32_bf16 v[62:65], v[212:215], v[208:211], v[62:65]
	v_mfma_f32_16x16x32_bf16 v[58:61], v[216:219], v[208:211], v[58:61]
	v_mfma_f32_16x16x32_bf16 v[54:57], v[220:223], v[208:211], v[54:57]
	v_mfma_f32_16x16x32_bf16 v[50:53], v[224:227], v[208:211], v[50:53]
	ds_read_b128 v[208:211], v0 offset:4096
	v_mfma_f32_16x16x32_bf16 v[46:49], v[212:215], v[238:241], v[46:49]
	v_mfma_f32_16x16x32_bf16 v[42:45], v[216:219], v[238:241], v[42:45]
	v_mfma_f32_16x16x32_bf16 v[38:41], v[220:223], v[238:241], v[38:41]
	v_mfma_f32_16x16x32_bf16 v[34:37], v[224:227], v[238:241], v[34:37]
	ds_read_b128 v[238:241], v0 offset:6144
	v_add_u32_e32 v191, v191, v190
	s_setprio 0
	s_cmpk_lg_i32 s20, 0x480
	s_cbranch_scc1 .LBB0_470
	v_and_b32_e32 v228, 15, v175
	v_bfe_u32 v229, v175, 8, 1
	v_lshl_or_b32 v228, v229, 7, v228
	v_mul_u32_u24_e32 v228, 0x210, v228
	v_bfe_u32 v229, v175, 6, 2
	v_lshl_add_u32 v228, v229, 7, v228
	v_bfe_u32 v229, v175, 4, 2
	v_lshl_add_u32 v228, v229, 3, v228
	v_cvt_pk_bf16_f32 v158, v158, v159
	v_cvt_pk_bf16_f32 v159, v160, v161
	v_cvt_pk_bf16_f32 v154, v154, v155
	v_cvt_pk_bf16_f32 v155, v156, v157
	v_cvt_pk_bf16_f32 v150, v150, v151
	v_cvt_pk_bf16_f32 v151, v152, v153
	v_cvt_pk_bf16_f32 v146, v146, v147
	v_cvt_pk_bf16_f32 v147, v148, v149
	ds_write_b64 v228, v[158:159]
	ds_write_b64 v228, v[154:155] offset:32
	ds_write_b64 v228, v[150:151] offset:64
	ds_write_b64 v228, v[146:147] offset:96
	v_cvt_pk_bf16_f32 v142, v142, v143
	v_cvt_pk_bf16_f32 v143, v144, v145
	v_cvt_pk_bf16_f32 v138, v138, v139
	v_cvt_pk_bf16_f32 v139, v140, v141
	v_cvt_pk_bf16_f32 v134, v134, v135
	v_cvt_pk_bf16_f32 v135, v136, v137
	v_cvt_pk_bf16_f32 v130, v130, v131
	v_cvt_pk_bf16_f32 v131, v132, v133
	ds_write_b64 v228, v[142:143] offset:8448
	ds_write_b64 v228, v[138:139] offset:8480
	ds_write_b64 v228, v[134:135] offset:8512
	ds_write_b64 v228, v[130:131] offset:8544
	v_cvt_pk_bf16_f32 v126, v126, v127
	v_cvt_pk_bf16_f32 v127, v128, v129
	v_cvt_pk_bf16_f32 v122, v122, v123
	v_cvt_pk_bf16_f32 v123, v124, v125
	v_cvt_pk_bf16_f32 v118, v118, v119
	v_cvt_pk_bf16_f32 v119, v120, v121
	v_cvt_pk_bf16_f32 v114, v114, v115
	v_cvt_pk_bf16_f32 v115, v116, v117
	ds_write_b64 v228, v[126:127] offset:16896
	ds_write_b64 v228, v[122:123] offset:16928
	ds_write_b64 v228, v[118:119] offset:16960
	ds_write_b64 v228, v[114:115] offset:16992
	v_cvt_pk_bf16_f32 v110, v110, v111
	v_cvt_pk_bf16_f32 v111, v112, v113
	v_cvt_pk_bf16_f32 v106, v106, v107
	v_cvt_pk_bf16_f32 v107, v108, v109
	v_cvt_pk_bf16_f32 v102, v102, v103
	v_cvt_pk_bf16_f32 v103, v104, v105
	v_cvt_pk_bf16_f32 v98, v98, v99
	v_cvt_pk_bf16_f32 v99, v100, v101
	ds_write_b64 v228, v[110:111] offset:25344
	ds_write_b64 v228, v[106:107] offset:25376
	ds_write_b64 v228, v[102:103] offset:25408
	ds_write_b64 v228, v[98:99] offset:25440
	v_cvt_pk_bf16_f32 v94, v94, v95
	v_cvt_pk_bf16_f32 v95, v96, v97
	v_cvt_pk_bf16_f32 v90, v90, v91
	v_cvt_pk_bf16_f32 v91, v92, v93
	v_cvt_pk_bf16_f32 v86, v86, v87
	v_cvt_pk_bf16_f32 v87, v88, v89
	v_cvt_pk_bf16_f32 v82, v82, v83
	v_cvt_pk_bf16_f32 v83, v84, v85
	ds_write_b64 v228, v[94:95] offset:33792
	ds_write_b64 v228, v[90:91] offset:33824
	ds_write_b64 v228, v[86:87] offset:33856
	ds_write_b64 v228, v[82:83] offset:33888
	v_cvt_pk_bf16_f32 v78, v78, v79
	v_cvt_pk_bf16_f32 v79, v80, v81
	v_cvt_pk_bf16_f32 v74, v74, v75
	v_cvt_pk_bf16_f32 v75, v76, v77
	v_cvt_pk_bf16_f32 v70, v70, v71
	v_cvt_pk_bf16_f32 v71, v72, v73
	v_cvt_pk_bf16_f32 v66, v66, v67
	v_cvt_pk_bf16_f32 v67, v68, v69
	ds_write_b64 v228, v[78:79] offset:42240
	ds_write_b64 v228, v[74:75] offset:42272
	ds_write_b64 v228, v[70:71] offset:42304
	ds_write_b64 v228, v[66:67] offset:42336
	v_cvt_pk_bf16_f32 v62, v62, v63
	v_cvt_pk_bf16_f32 v63, v64, v65
	v_cvt_pk_bf16_f32 v58, v58, v59
	v_cvt_pk_bf16_f32 v59, v60, v61
	v_cvt_pk_bf16_f32 v54, v54, v55
	v_cvt_pk_bf16_f32 v55, v56, v57
	v_cvt_pk_bf16_f32 v50, v50, v51
	v_cvt_pk_bf16_f32 v51, v52, v53
	ds_write_b64 v228, v[62:63] offset:50688
	ds_write_b64 v228, v[58:59] offset:50720
	ds_write_b64 v228, v[54:55] offset:50752
	ds_write_b64 v228, v[50:51] offset:50784
	v_cvt_pk_bf16_f32 v46, v46, v47
	v_cvt_pk_bf16_f32 v47, v48, v49
	v_cvt_pk_bf16_f32 v42, v42, v43
	v_cvt_pk_bf16_f32 v43, v44, v45
	v_cvt_pk_bf16_f32 v38, v38, v39
	v_cvt_pk_bf16_f32 v39, v40, v41
	v_cvt_pk_bf16_f32 v34, v34, v35
	v_cvt_pk_bf16_f32 v35, v36, v37
	ds_write_b64 v228, v[46:47] offset:59136
	ds_write_b64 v228, v[42:43] offset:59168
	ds_write_b64 v228, v[38:39] offset:59200
	ds_write_b64 v228, v[34:35] offset:59232
	v_mov_b32_e32 v43, v175
	s_waitcnt lgkmcnt(0)
	s_barrier
; #define RTID opaque_tid()
; __device__ __forceinline__ void phase_win(const Params& p, int part, u16* smem, volatile LAS unsigned* vb_) {
;     ...
;     const int tid2 = RTID;
; #pragma unroll
;     for (int k = 0; k < 16; ++k) {
;       const int c = tid2 + 512 * k;
;       const int row = c >> 5, ch = c & 31;
;       const uint4 v = *(const uint4*)(smem + row * 264 + ch * 8);
;       u16* d_ = (ch < 16) ? dstA : dstB;
;       const int l_ = (ch < 16) ? ldA : ldB;
;       *(uint4*)(d_ + (size_t)(mt * 256 + row) * l_ + (ch & 15) * 8) = v;
;     }
;     __syncthreads();
	s_mov_b32 s38, s36
	v_and_b32_e32 v0, 31, v43
	v_lshlrev_b32_e32 v42, 4, v0
	v_cmp_gt_u32_e32 vcc, 16, v0
	v_mov_b32_e32 v0, 0x100
	s_nop 0
	v_cndmask_b32_e64 v0, v0, 0, vcc
	v_lshl_add_u64 v[34:35], s[44:45], 0, v[0:1]
	v_lshlrev_b32_e32 v0, 4, v43
	v_and_b32_e32 v0, 0xf0, v0
	v_lshl_add_u64 v[44:45], v[34:35], 0, v[0:1]
	v_ashrrev_i32_e32 v0, 5, v43
	v_mad_u64_u32 v[34:35], s[12:13], v0, s2, v[42:43]
	v_add_u32_e32 v0, s10, v0
	ds_read_b128 v[34:37], v34
	v_ashrrev_i32_e32 v38, 31, v0
	v_mul_lo_u32 v40, s0, v38
	v_mul_lo_u32 v41, s1, v0
	v_mad_u64_u32 v[38:39], s[12:13], s0, v0, 0
	v_add_u32_e32 v0, 0x200, v43
	v_add3_u32 v39, v39, v40, v41
	v_ashrrev_i32_e32 v0, 5, v0
	v_lshl_add_u64 v[46:47], v[38:39], 1, v[44:45]
	v_mad_u64_u32 v[38:39], s[12:13], v0, s2, v[42:43]
	ds_read_b128 v[38:41], v38
	v_add_u32_e32 v0, s10, v0
	s_waitcnt lgkmcnt(1)
	global_store_dwordx4 v[46:47], v[34:37], off
	s_and_b64 vcc, exec, s[42:43]
	s_nop 0
	v_ashrrev_i32_e32 v34, 31, v0
	v_mul_lo_u32 v36, s0, v34
	v_mul_lo_u32 v37, s1, v0
	v_mad_u64_u32 v[34:35], s[12:13], s0, v0, 0
	v_add3_u32 v35, v35, v36, v37
	v_add_u32_e32 v0, 0x400, v43
	v_lshl_add_u64 v[34:35], v[34:35], 1, v[44:45]
	v_ashrrev_i32_e32 v0, 5, v0
	s_waitcnt lgkmcnt(0)
	global_store_dwordx4 v[34:35], v[38:41], off
	v_mad_u64_u32 v[34:35], s[12:13], v0, s2, v[42:43]
	v_add_u32_e32 v0, s10, v0
	ds_read_b128 v[34:37], v34
	v_ashrrev_i32_e32 v38, 31, v0
	v_mul_lo_u32 v40, s0, v38
	v_mul_lo_u32 v41, s1, v0
	v_mad_u64_u32 v[38:39], s[12:13], s0, v0, 0
	v_add_u32_e32 v0, 0x600, v43
	v_add3_u32 v39, v39, v40, v41
	v_ashrrev_i32_e32 v0, 5, v0
	v_lshl_add_u64 v[46:47], v[38:39], 1, v[44:45]
	v_mad_u64_u32 v[38:39], s[12:13], v0, s2, v[42:43]
	ds_read_b128 v[38:41], v38
	v_add_u32_e32 v0, s10, v0
	s_waitcnt lgkmcnt(1)
	global_store_dwordx4 v[46:47], v[34:37], off
	s_nop 1
	v_ashrrev_i32_e32 v34, 31, v0
	v_mul_lo_u32 v36, s0, v34
	v_mul_lo_u32 v37, s1, v0
	v_mad_u64_u32 v[34:35], s[12:13], s0, v0, 0
	v_add3_u32 v35, v35, v36, v37
	v_add_u32_e32 v0, 0x800, v43
	v_lshl_add_u64 v[34:35], v[34:35], 1, v[44:45]
	v_ashrrev_i32_e32 v0, 5, v0
	s_waitcnt lgkmcnt(0)
	global_store_dwordx4 v[34:35], v[38:41], off
	v_mad_u64_u32 v[34:35], s[12:13], v0, s2, v[42:43]
	v_add_u32_e32 v0, s10, v0
	ds_read_b128 v[34:37], v34
	v_ashrrev_i32_e32 v38, 31, v0
	v_mul_lo_u32 v40, s0, v38
	v_mul_lo_u32 v41, s1, v0
	v_mad_u64_u32 v[38:39], s[12:13], s0, v0, 0
	v_add_u32_e32 v0, 0xa00, v43
	v_add3_u32 v39, v39, v40, v41
	v_ashrrev_i32_e32 v0, 5, v0
	v_lshl_add_u64 v[46:47], v[38:39], 1, v[44:45]
	v_mad_u64_u32 v[38:39], s[12:13], v0, s2, v[42:43]
	ds_read_b128 v[38:41], v38
	v_add_u32_e32 v0, s10, v0
	s_waitcnt lgkmcnt(1)
	global_store_dwordx4 v[46:47], v[34:37], off
	s_nop 1
	v_ashrrev_i32_e32 v34, 31, v0
	v_mul_lo_u32 v36, s0, v34
	v_mul_lo_u32 v37, s1, v0
	v_mad_u64_u32 v[34:35], s[12:13], s0, v0, 0
	v_add3_u32 v35, v35, v36, v37
	v_add_u32_e32 v0, 0xc00, v43
	v_lshl_add_u64 v[34:35], v[34:35], 1, v[44:45]
	v_ashrrev_i32_e32 v0, 5, v0
	s_waitcnt lgkmcnt(0)
	global_store_dwordx4 v[34:35], v[38:41], off
	v_mad_u64_u32 v[34:35], s[12:13], v0, s2, v[42:43]
	v_add_u32_e32 v0, s10, v0
	ds_read_b128 v[34:37], v34
	v_ashrrev_i32_e32 v38, 31, v0
	v_mul_lo_u32 v40, s0, v38
	v_mul_lo_u32 v41, s1, v0
	v_mad_u64_u32 v[38:39], s[12:13], s0, v0, 0
	v_add_u32_e32 v0, 0xe00, v43
	v_add3_u32 v39, v39, v40, v41
	v_ashrrev_i32_e32 v0, 5, v0
	v_lshl_add_u64 v[46:47], v[38:39], 1, v[44:45]
	v_mad_u64_u32 v[38:39], s[12:13], v0, s2, v[42:43]
	ds_read_b128 v[38:41], v38
	v_add_u32_e32 v0, s10, v0
	s_waitcnt lgkmcnt(1)
	global_store_dwordx4 v[46:47], v[34:37], off
	s_nop 1
	v_ashrrev_i32_e32 v34, 31, v0
	v_mul_lo_u32 v36, s0, v34
	v_mul_lo_u32 v37, s1, v0
	v_mad_u64_u32 v[34:35], s[12:13], s0, v0, 0
	v_add3_u32 v35, v35, v36, v37
	v_add_u32_e32 v0, 0x1000, v43
	v_lshl_add_u64 v[34:35], v[34:35], 1, v[44:45]
	v_ashrrev_i32_e32 v0, 5, v0
	s_waitcnt lgkmcnt(0)
; #define RTID opaque_tid()
; __device__ __forceinline__ void phase_win(const Params& p, int part, u16* smem, volatile LAS unsigned* vb_) {
;     ...
;     const int tid2 = RTID;
; #pragma unroll
;     for (int k = 0; k < 16; ++k) {
;       const int c = tid2 + 512 * k;
;       const int row = c >> 5, ch = c & 31;
;       const uint4 v = *(const uint4*)(smem + row * 264 + ch * 8);
;       u16* d_ = (ch < 16) ? dstA : dstB;
;       const int l_ = (ch < 16) ? ldA : ldB;
;       *(uint4*)(d_ + (size_t)(mt * 256 + row) * l_ + (ch & 15) * 8) = v;
;     }
;     __syncthreads();
	global_store_dwordx4 v[34:35], v[38:41], off
	v_mad_u64_u32 v[34:35], s[12:13], v0, s2, v[42:43]
	v_add_u32_e32 v0, s10, v0
	ds_read_b128 v[34:37], v34
	v_ashrrev_i32_e32 v38, 31, v0
	v_mul_lo_u32 v40, s0, v38
	v_mul_lo_u32 v41, s1, v0
	v_mad_u64_u32 v[38:39], s[12:13], s0, v0, 0
	v_add_u32_e32 v0, 0x1200, v43
	v_add3_u32 v39, v39, v40, v41
	v_ashrrev_i32_e32 v0, 5, v0
	v_lshl_add_u64 v[46:47], v[38:39], 1, v[44:45]
	v_mad_u64_u32 v[38:39], s[12:13], v0, s2, v[42:43]
	ds_read_b128 v[38:41], v38
	v_add_u32_e32 v0, s10, v0
	s_waitcnt lgkmcnt(1)
	global_store_dwordx4 v[46:47], v[34:37], off
	s_nop 1
	v_ashrrev_i32_e32 v34, 31, v0
	v_mul_lo_u32 v36, s0, v34
	v_mul_lo_u32 v37, s1, v0
	v_mad_u64_u32 v[34:35], s[12:13], s0, v0, 0
	v_add3_u32 v35, v35, v36, v37
	v_add_u32_e32 v0, 0x1400, v43
	v_lshl_add_u64 v[34:35], v[34:35], 1, v[44:45]
	v_ashrrev_i32_e32 v0, 5, v0
	s_waitcnt lgkmcnt(0)
	global_store_dwordx4 v[34:35], v[38:41], off
	v_mad_u64_u32 v[34:35], s[12:13], v0, s2, v[42:43]
	v_add_u32_e32 v0, s10, v0
	ds_read_b128 v[34:37], v34
	v_ashrrev_i32_e32 v38, 31, v0
	v_mul_lo_u32 v40, s0, v38
	v_mul_lo_u32 v41, s1, v0
	v_mad_u64_u32 v[38:39], s[12:13], s0, v0, 0
	v_add_u32_e32 v0, 0x1600, v43
	v_add3_u32 v39, v39, v40, v41
	v_ashrrev_i32_e32 v0, 5, v0
	v_lshl_add_u64 v[46:47], v[38:39], 1, v[44:45]
	v_mad_u64_u32 v[38:39], s[12:13], v0, s2, v[42:43]
	ds_read_b128 v[38:41], v38
	v_add_u32_e32 v0, s10, v0
	s_waitcnt lgkmcnt(1)
	global_store_dwordx4 v[46:47], v[34:37], off
	s_nop 1
	v_ashrrev_i32_e32 v34, 31, v0
	v_mul_lo_u32 v36, s0, v34
	v_mul_lo_u32 v37, s1, v0
	v_mad_u64_u32 v[34:35], s[12:13], s0, v0, 0
	v_add3_u32 v35, v35, v36, v37
	v_add_u32_e32 v0, 0x1800, v43
	v_lshl_add_u64 v[34:35], v[34:35], 1, v[44:45]
	v_ashrrev_i32_e32 v0, 5, v0
	s_waitcnt lgkmcnt(0)
	global_store_dwordx4 v[34:35], v[38:41], off
	v_mad_u64_u32 v[34:35], s[12:13], v0, s2, v[42:43]
	v_add_u32_e32 v0, s10, v0
	ds_read_b128 v[34:37], v34
	v_ashrrev_i32_e32 v38, 31, v0
	v_mul_lo_u32 v40, s0, v38
	v_mul_lo_u32 v41, s1, v0
	v_mad_u64_u32 v[38:39], s[12:13], s0, v0, 0
	v_add_u32_e32 v0, 0x1a00, v43
	v_add3_u32 v39, v39, v40, v41
	v_ashrrev_i32_e32 v0, 5, v0
	v_lshl_add_u64 v[46:47], v[38:39], 1, v[44:45]
	v_mad_u64_u32 v[38:39], s[12:13], v0, s2, v[42:43]
	ds_read_b128 v[38:41], v38
	v_add_u32_e32 v0, s10, v0
	s_waitcnt lgkmcnt(1)
	global_store_dwordx4 v[46:47], v[34:37], off
	s_nop 1
	v_ashrrev_i32_e32 v34, 31, v0
	v_mul_lo_u32 v36, s0, v34
	v_mul_lo_u32 v37, s1, v0
	v_mad_u64_u32 v[34:35], s[12:13], s0, v0, 0
	v_add3_u32 v35, v35, v36, v37
	v_add_u32_e32 v0, 0x1c00, v43
	v_lshl_add_u64 v[34:35], v[34:35], 1, v[44:45]
	v_ashrrev_i32_e32 v0, 5, v0
	s_waitcnt lgkmcnt(0)
	global_store_dwordx4 v[34:35], v[38:41], off
	v_mad_u64_u32 v[34:35], s[12:13], v0, s2, v[42:43]
	v_add_u32_e32 v0, s10, v0
	ds_read_b128 v[34:37], v34
	v_ashrrev_i32_e32 v38, 31, v0
	v_mul_lo_u32 v40, s0, v38
	v_mul_lo_u32 v41, s1, v0
	v_mad_u64_u32 v[38:39], s[12:13], s0, v0, 0
	v_add_u32_e32 v0, 0x1e00, v43
	v_add3_u32 v39, v39, v40, v41
	v_ashrrev_i32_e32 v0, 5, v0
	v_lshl_add_u64 v[46:47], v[38:39], 1, v[44:45]
	v_mad_u64_u32 v[38:39], s[12:13], v0, s2, v[42:43]
	ds_read_b128 v[38:41], v38
	v_add_u32_e32 v0, s10, v0
	s_waitcnt lgkmcnt(1)
	global_store_dwordx4 v[46:47], v[34:37], off
	s_mov_b64 s[12:13], -1
	s_nop 0
	v_ashrrev_i32_e32 v34, 31, v0
	v_mul_lo_u32 v36, s0, v34
	v_mul_lo_u32 v37, s1, v0
	v_mad_u64_u32 v[34:35], s[0:1], s0, v0, 0
	v_add3_u32 v35, v35, v36, v37
	v_lshl_add_u64 v[34:35], v[34:35], 1, v[44:45]
	s_waitcnt lgkmcnt(0)
	global_store_dwordx4 v[34:35], v[38:41], off
	s_barrier
	s_cbranch_vccz .LBB0_441

; template <int MI, int NJ> ...
;     ...
;   for (int kt = 0; kt < nk; ++kt) {
;     const int buf = kt & 1;
;     {
;       G8STORE(buf ^ 1);
;       const u16* ga_ = (kt + 2 < nk) ? Ag + (kt + 2) * 64 : Ag + nAoff;
;       const u16* gb_ = (kt + 2 < nk) ? Bg + (kt + 2) * 64 : Bg + nBoff;
;       G8LOADP(ga_, gb_);
;     }
;     __builtin_amdgcn_sched_barrier(0);
;     __builtin_amdgcn_s_setprio(1);
;     const u16* a = ra_ + buf * AROWS * 64;
;     const u16* b = rb_ + buf * BROWS * 64;
; #pragma unroll
;     for (int ks = 0; ks < 2; ++ks) {
;       const u16* a_ = ks ? a + dsw : a;
;       const u16* b_ = ks ? b + dsw : b;
;       bf16x8 bfr[NJ];
; #pragma unroll
;       for (int j = 0; j < NJ; ++j) bfr[j] = *(const bf16x8*)(b_ + j * 16 * 64);
; #pragma unroll
;       for (int ih = 0; ih < MI / 4; ++ih) {
;         bf16x8 af[4];
; #pragma unroll
;         for (int i = 0; i < 4; ++i) af[i] = *(const bf16x8*)(a_ + (ih * 4 + i) * 16 * 64);
; #pragma unroll
;         for (int i = 0; i < 4; ++i)
; #pragma unroll
;           for (int j = 0; j < NJ; ++j) acc[ih * 4 + i][j] = mfma16(af[i], bfr[j], acc[ih * 4 + i][j]);
;       }
;     }
;     __builtin_amdgcn_s_setprio(0);
;     __builtin_amdgcn_sched_barrier(0);
;     __syncthreads();
;   }
.LBB0_481:
	s_setprio 1
	s_waitcnt lgkmcnt(6)
	v_mfma_f32_16x16x32_bf16 v[158:161], v[166:169], v[162:165], v[158:161]
	s_waitcnt lgkmcnt(5)
	v_mfma_f32_16x16x32_bf16 v[154:157], v[170:173], v[162:165], v[154:157]
	s_waitcnt lgkmcnt(4)
	v_mfma_f32_16x16x32_bf16 v[150:153], v[192:195], v[162:165], v[150:153]
	s_waitcnt lgkmcnt(3)
	v_mfma_f32_16x16x32_bf16 v[146:149], v[196:199], v[162:165], v[146:149]
	ds_read_b128 v[162:165], v0 offset:8192
	s_waitcnt lgkmcnt(3)
	v_mfma_f32_16x16x32_bf16 v[142:145], v[166:169], v[204:207], v[142:145]
	v_mfma_f32_16x16x32_bf16 v[138:141], v[170:173], v[204:207], v[138:141]
	v_mfma_f32_16x16x32_bf16 v[134:137], v[192:195], v[204:207], v[134:137]
	v_mfma_f32_16x16x32_bf16 v[130:133], v[196:199], v[204:207], v[130:133]
	ds_read_b128 v[204:207], v0 offset:10240
	s_waitcnt lgkmcnt(3)
	v_mfma_f32_16x16x32_bf16 v[126:129], v[166:169], v[208:211], v[126:129]
	v_mfma_f32_16x16x32_bf16 v[122:125], v[170:173], v[208:211], v[122:125]
	v_mfma_f32_16x16x32_bf16 v[118:121], v[192:195], v[208:211], v[118:121]
	v_mfma_f32_16x16x32_bf16 v[114:117], v[196:199], v[208:211], v[114:117]
	ds_read_b128 v[208:211], v0 offset:12288
	ds_read_b128 v[212:215], v191
	ds_read_b128 v[216:219], v191 offset:2048
	s_waitcnt lgkmcnt(5)
	v_mfma_f32_16x16x32_bf16 v[110:113], v[166:169], v[238:241], v[110:113]
	v_mfma_f32_16x16x32_bf16 v[106:109], v[170:173], v[238:241], v[106:109]
	v_mfma_f32_16x16x32_bf16 v[102:105], v[192:195], v[238:241], v[102:105]
	v_mfma_f32_16x16x32_bf16 v[98:101], v[196:199], v[238:241], v[98:101]
	ds_read_b128 v[238:241], v0 offset:14336
	ds_read_b128 v[220:223], v191 offset:4096
	ds_read_b128 v[224:227], v191 offset:6144
	s_waitcnt lgkmcnt(7)
	v_mfma_f32_16x16x32_bf16 v[94:97], v[166:169], v[162:165], v[94:97]
	v_mfma_f32_16x16x32_bf16 v[90:93], v[170:173], v[162:165], v[90:93]
	v_mfma_f32_16x16x32_bf16 v[86:89], v[192:195], v[162:165], v[86:89]
	v_mfma_f32_16x16x32_bf16 v[82:85], v[196:199], v[162:165], v[82:85]
	v_add_u32_e32 v0, v0, v190
	ds_read_b128 v[162:165], v0
	s_waitcnt vmcnt(7)
	ds_write_b128 v228, v[10:13]
	global_load_dwordx4 v[10:13], v234, s[50:51]
	s_waitcnt lgkmcnt(8)
	v_mfma_f32_16x16x32_bf16 v[78:81], v[166:169], v[204:207], v[78:81]
	v_mfma_f32_16x16x32_bf16 v[70:73], v[170:173], v[204:207], v[70:73]
	v_mfma_f32_16x16x32_bf16 v[66:69], v[192:195], v[204:207], v[66:69]
	v_mfma_f32_16x16x32_bf16 v[58:61], v[196:199], v[204:207], v[58:61]
	ds_read_b128 v[204:207], v0 offset:2048
	s_waitcnt vmcnt(7)
	ds_write_b128 v228, v[2:5] offset:8192
	global_load_dwordx4 v[2:5], v235, s[50:51]
	s_waitcnt lgkmcnt(9)
	v_mfma_f32_16x16x32_bf16 v[54:57], v[166:169], v[208:211], v[54:57]
	v_mfma_f32_16x16x32_bf16 v[50:53], v[170:173], v[208:211], v[50:53]
	v_mfma_f32_16x16x32_bf16 v[46:49], v[192:195], v[208:211], v[46:49]
	v_mfma_f32_16x16x32_bf16 v[38:41], v[196:199], v[208:211], v[38:41]
	ds_read_b128 v[208:211], v0 offset:4096
	s_waitcnt vmcnt(7)
	ds_write_b128 v228, v[6:9] offset:16384
	global_load_dwordx4 v[6:9], v236, s[50:51]
	s_waitcnt lgkmcnt(8)
	v_mfma_f32_16x16x32_bf16 v[34:37], v[166:169], v[238:241], v[34:37]
	v_mfma_f32_16x16x32_bf16 v[30:33], v[170:173], v[238:241], v[30:33]
	v_mfma_f32_16x16x32_bf16 v[26:29], v[192:195], v[238:241], v[26:29]
	v_mfma_f32_16x16x32_bf16 v[22:25], v[196:199], v[238:241], v[22:25]
	ds_read_b128 v[238:241], v0 offset:6144
	s_waitcnt vmcnt(7)
	ds_write_b128 v228, v[14:17] offset:24576
	global_load_dwordx4 v[14:17], v237, s[50:51]
	s_waitcnt lgkmcnt(7)
	v_mfma_f32_16x16x32_bf16 v[158:161], v[212:215], v[162:165], v[158:161]
	v_mfma_f32_16x16x32_bf16 v[154:157], v[216:219], v[162:165], v[154:157]
	v_mfma_f32_16x16x32_bf16 v[150:153], v[220:223], v[162:165], v[150:153]
	v_mfma_f32_16x16x32_bf16 v[146:149], v[224:227], v[162:165], v[146:149]
	ds_read_b128 v[162:165], v0 offset:8192
	s_waitcnt vmcnt(7)
	ds_write_b128 v229, v[18:21]
	global_load_dwordx4 v[18:21], v234, s[52:53]
	s_waitcnt lgkmcnt(7)
	v_mfma_f32_16x16x32_bf16 v[142:145], v[212:215], v[204:207], v[142:145]
	v_mfma_f32_16x16x32_bf16 v[138:141], v[216:219], v[204:207], v[138:141]
	v_mfma_f32_16x16x32_bf16 v[134:137], v[220:223], v[204:207], v[134:137]
	v_mfma_f32_16x16x32_bf16 v[130:133], v[224:227], v[204:207], v[130:133]
	ds_read_b128 v[204:207], v0 offset:10240
	s_waitcnt vmcnt(7)
	ds_write_b128 v229, v[42:45] offset:8192
	global_load_dwordx4 v[42:45], v235, s[52:53]
	s_waitcnt lgkmcnt(7)
	v_mfma_f32_16x16x32_bf16 v[126:129], v[212:215], v[208:211], v[126:129]
	v_mfma_f32_16x16x32_bf16 v[122:125], v[216:219], v[208:211], v[122:125]
	v_mfma_f32_16x16x32_bf16 v[118:121], v[220:223], v[208:211], v[118:121]
	v_mfma_f32_16x16x32_bf16 v[114:117], v[224:227], v[208:211], v[114:117]
	ds_read_b128 v[208:211], v0 offset:12288
	s_waitcnt vmcnt(7)
	ds_write_b128 v229, v[62:65] offset:16384
	global_load_dwordx4 v[62:65], v236, s[52:53]
	s_waitcnt lgkmcnt(7)
	v_mfma_f32_16x16x32_bf16 v[110:113], v[212:215], v[238:241], v[110:113]
	v_mfma_f32_16x16x32_bf16 v[106:109], v[216:219], v[238:241], v[106:109]
	v_mfma_f32_16x16x32_bf16 v[102:105], v[220:223], v[238:241], v[102:105]
	v_mfma_f32_16x16x32_bf16 v[98:101], v[224:227], v[238:241], v[98:101]
	ds_read_b128 v[238:241], v0 offset:14336
	s_waitcnt vmcnt(7)
	ds_write_b128 v229, v[74:77] offset:24576
	global_load_dwordx4 v[74:77], v237, s[52:53]
	s_waitcnt lgkmcnt(7)
	v_mfma_f32_16x16x32_bf16 v[94:97], v[212:215], v[162:165], v[94:97]
	v_mfma_f32_16x16x32_bf16 v[90:93], v[216:219], v[162:165], v[90:93]
	v_mfma_f32_16x16x32_bf16 v[86:89], v[220:223], v[162:165], v[86:89]
	v_mfma_f32_16x16x32_bf16 v[82:85], v[224:227], v[162:165], v[82:85]
	s_waitcnt lgkmcnt(0)
	s_setprio 0
	s_barrier
; template <int MI, int NJ> ...
;     ...
;   for (int kt = 0; kt < nk; ++kt) {
;     const int buf = kt & 1;
;     {
;       G8STORE(buf ^ 1);
;       const u16* ga_ = (kt + 2 < nk) ? Ag + (kt + 2) * 64 : Ag + nAoff;
;       const u16* gb_ = (kt + 2 < nk) ? Bg + (kt + 2) * 64 : Bg + nBoff;
;       G8LOADP(ga_, gb_);
;     }
;     __builtin_amdgcn_sched_barrier(0);
;     __builtin_amdgcn_s_setprio(1);
;     const u16* a = ra_ + buf * AROWS * 64;
;     const u16* b = rb_ + buf * BROWS * 64;
; #pragma unroll
;     for (int ks = 0; ks < 2; ++ks) {
;       const u16* a_ = ks ? a + dsw : a;
;       const u16* b_ = ks ? b + dsw : b;
;       bf16x8 bfr[NJ];
; #pragma unroll
;       for (int j = 0; j < NJ; ++j) bfr[j] = *(const bf16x8*)(b_ + j * 16 * 64);
; #pragma unroll
;       for (int ih = 0; ih < MI / 4; ++ih) {
;         bf16x8 af[4];
; #pragma unroll
;         for (int i = 0; i < 4; ++i) af[i] = *(const bf16x8*)(a_ + (ih * 4 + i) * 16 * 64);
; #pragma unroll
;         for (int i = 0; i < 4; ++i)
; #pragma unroll
;           for (int j = 0; j < NJ; ++j) acc[ih * 4 + i][j] = mfma16(af[i], bfr[j], acc[ih * 4 + i][j]);
;       }
;     }
;     __builtin_amdgcn_s_setprio(0);
;     __builtin_amdgcn_sched_barrier(0);
;     __syncthreads();
;   }
; __device__ __forceinline__ void phase_gemm_f32(const u16* A, const u16* Bt, int K, u16* out, u16* smem,
;                                                volatile LAS unsigned* vb_) {
;     ...
; #pragma unroll
;     for (int i = 0; i < 8; ++i)
; #pragma unroll
;       for (int j = 0; j < 4; ++j)
; #pragma unroll
;         for (int r = 0; r < 4; ++r)
;           smem[(wm * 128 + i * 16 + (lane >> 4) * 4 + r) * 264 + wn * 64 + j * 16 + (lane & 15)] = f2bf(acc[i][j][r]);
;     __syncthreads();
	s_add_i32 s44, s44, 1
	s_add_i32 s39, s39, 64
	s_addk_i32 s43, 0x4000
	s_and_b32 s45, s43, 0x4000
	s_xor_b32 s46, s45, 0x4000
	s_lshl_b32 s46, s46, 1
	v_add_u32_e32 v228, s46, v185
	v_add_u32_e32 v229, s46, v186
	s_add_i32 s46, s44, 2
	s_cmp_lt_u32 s46, s21
	s_cselect_b32 s47, 0, s12
	s_cselect_b32 s46, s39, s13
	s_cselect_b32 s49, 0, s37
	s_cselect_b32 s48, s39, s38
	s_lshl_b64 s[46:47], s[46:47], 1
	s_lshl_b64 s[48:49], s[48:49], 1
	s_add_u32 s50, s62, s46
	s_addc_u32 s51, s63, s47
	s_add_u32 s52, s64, s48
	s_addc_u32 s53, s65, s49
	s_lshl_b32 s45, s45, 1
	v_add_u32_e32 v0, s45, v187
	v_add_u32_e32 v191, s45, v188
	s_setprio 1
	ds_read_b128 v[166:169], v191
	ds_read_b128 v[162:165], v0
	ds_read_b128 v[170:173], v191 offset:2048
	ds_read_b128 v[192:195], v191 offset:4096
	ds_read_b128 v[196:199], v191 offset:6144
	v_mfma_f32_16x16x32_bf16 v[78:81], v[212:215], v[204:207], v[78:81]
	v_mfma_f32_16x16x32_bf16 v[70:73], v[216:219], v[204:207], v[70:73]
	v_mfma_f32_16x16x32_bf16 v[66:69], v[220:223], v[204:207], v[66:69]
	v_mfma_f32_16x16x32_bf16 v[58:61], v[224:227], v[204:207], v[58:61]
	ds_read_b128 v[204:207], v0 offset:2048
	v_mfma_f32_16x16x32_bf16 v[54:57], v[212:215], v[208:211], v[54:57]
	v_mfma_f32_16x16x32_bf16 v[50:53], v[216:219], v[208:211], v[50:53]
	v_mfma_f32_16x16x32_bf16 v[46:49], v[220:223], v[208:211], v[46:49]
	v_mfma_f32_16x16x32_bf16 v[38:41], v[224:227], v[208:211], v[38:41]
	ds_read_b128 v[208:211], v0 offset:4096
	v_mfma_f32_16x16x32_bf16 v[34:37], v[212:215], v[238:241], v[34:37]
	v_mfma_f32_16x16x32_bf16 v[30:33], v[216:219], v[238:241], v[30:33]
	v_mfma_f32_16x16x32_bf16 v[26:29], v[220:223], v[238:241], v[26:29]
	v_mfma_f32_16x16x32_bf16 v[22:25], v[224:227], v[238:241], v[22:25]
	ds_read_b128 v[238:241], v0 offset:6144
	v_add_u32_e32 v191, v191, v190
	s_setprio 0
	s_cmp_lg_u32 s21, s44
	s_cbranch_scc1 .LBB0_481
	v_and_b32_e32 v228, 15, v175
	v_bfe_u32 v229, v175, 8, 1
	v_lshl_or_b32 v228, v229, 7, v228
	v_mul_u32_u24_e32 v228, 0x210, v228
	v_bfe_u32 v229, v175, 6, 2
	v_lshl_add_u32 v228, v229, 7, v228
	v_bfe_u32 v229, v175, 4, 2
	v_lshl_add_u32 v228, v229, 3, v228
	v_cvt_pk_bf16_f32 v158, v158, v159
	v_cvt_pk_bf16_f32 v159, v160, v161
	v_cvt_pk_bf16_f32 v154, v154, v155
	v_cvt_pk_bf16_f32 v155, v156, v157
	v_cvt_pk_bf16_f32 v150, v150, v151
	v_cvt_pk_bf16_f32 v151, v152, v153
	v_cvt_pk_bf16_f32 v146, v146, v147
	v_cvt_pk_bf16_f32 v147, v148, v149
	ds_write_b64 v228, v[158:159]
	ds_write_b64 v228, v[154:155] offset:32
	ds_write_b64 v228, v[150:151] offset:64
	ds_write_b64 v228, v[146:147] offset:96
	v_cvt_pk_bf16_f32 v142, v142, v143
	v_cvt_pk_bf16_f32 v143, v144, v145
	v_cvt_pk_bf16_f32 v138, v138, v139
	v_cvt_pk_bf16_f32 v139, v140, v141
	v_cvt_pk_bf16_f32 v134, v134, v135
	v_cvt_pk_bf16_f32 v135, v136, v137
	v_cvt_pk_bf16_f32 v130, v130, v131
	v_cvt_pk_bf16_f32 v131, v132, v133
	ds_write_b64 v228, v[142:143] offset:8448
	ds_write_b64 v228, v[138:139] offset:8480
	ds_write_b64 v228, v[134:135] offset:8512
	ds_write_b64 v228, v[130:131] offset:8544
	v_cvt_pk_bf16_f32 v126, v126, v127
	v_cvt_pk_bf16_f32 v127, v128, v129
	v_cvt_pk_bf16_f32 v122, v122, v123
	v_cvt_pk_bf16_f32 v123, v124, v125
	v_cvt_pk_bf16_f32 v118, v118, v119
	v_cvt_pk_bf16_f32 v119, v120, v121
	v_cvt_pk_bf16_f32 v114, v114, v115
	v_cvt_pk_bf16_f32 v115, v116, v117
	ds_write_b64 v228, v[126:127] offset:16896
	ds_write_b64 v228, v[122:123] offset:16928
	ds_write_b64 v228, v[118:119] offset:16960
	ds_write_b64 v228, v[114:115] offset:16992
	v_cvt_pk_bf16_f32 v110, v110, v111
	v_cvt_pk_bf16_f32 v111, v112, v113
	v_cvt_pk_bf16_f32 v106, v106, v107
	v_cvt_pk_bf16_f32 v107, v108, v109
	v_cvt_pk_bf16_f32 v102, v102, v103
	v_cvt_pk_bf16_f32 v103, v104, v105
	v_cvt_pk_bf16_f32 v98, v98, v99
	v_cvt_pk_bf16_f32 v99, v100, v101
	ds_write_b64 v228, v[110:111] offset:25344
	ds_write_b64 v228, v[106:107] offset:25376
	ds_write_b64 v228, v[102:103] offset:25408
	ds_write_b64 v228, v[98:99] offset:25440
	v_cvt_pk_bf16_f32 v94, v94, v95
	v_cvt_pk_bf16_f32 v95, v96, v97
	v_cvt_pk_bf16_f32 v90, v90, v91
	v_cvt_pk_bf16_f32 v91, v92, v93
	v_cvt_pk_bf16_f32 v86, v86, v87
	v_cvt_pk_bf16_f32 v87, v88, v89
	v_cvt_pk_bf16_f32 v82, v82, v83
	v_cvt_pk_bf16_f32 v83, v84, v85
	ds_write_b64 v228, v[94:95] offset:33792
	ds_write_b64 v228, v[90:91] offset:33824
	ds_write_b64 v228, v[86:87] offset:33856
	ds_write_b64 v228, v[82:83] offset:33888
	v_cvt_pk_bf16_f32 v78, v78, v79
	v_cvt_pk_bf16_f32 v79, v80, v81
	v_cvt_pk_bf16_f32 v70, v70, v71
	v_cvt_pk_bf16_f32 v71, v72, v73
	v_cvt_pk_bf16_f32 v66, v66, v67
	v_cvt_pk_bf16_f32 v67, v68, v69
	v_cvt_pk_bf16_f32 v58, v58, v59
	v_cvt_pk_bf16_f32 v59, v60, v61
	ds_write_b64 v228, v[78:79] offset:42240
	ds_write_b64 v228, v[70:71] offset:42272
	ds_write_b64 v228, v[66:67] offset:42304
	ds_write_b64 v228, v[58:59] offset:42336
	v_cvt_pk_bf16_f32 v54, v54, v55
	v_cvt_pk_bf16_f32 v55, v56, v57
	v_cvt_pk_bf16_f32 v50, v50, v51
	v_cvt_pk_bf16_f32 v51, v52, v53
	v_cvt_pk_bf16_f32 v46, v46, v47
	v_cvt_pk_bf16_f32 v47, v48, v49
	v_cvt_pk_bf16_f32 v38, v38, v39
	v_cvt_pk_bf16_f32 v39, v40, v41
	ds_write_b64 v228, v[54:55] offset:50688
	ds_write_b64 v228, v[50:51] offset:50720
	ds_write_b64 v228, v[46:47] offset:50752
	ds_write_b64 v228, v[38:39] offset:50784
	v_cvt_pk_bf16_f32 v34, v34, v35
	v_cvt_pk_bf16_f32 v35, v36, v37
	v_cvt_pk_bf16_f32 v30, v30, v31
	v_cvt_pk_bf16_f32 v31, v32, v33
	v_cvt_pk_bf16_f32 v26, v26, v27
	v_cvt_pk_bf16_f32 v27, v28, v29
	v_cvt_pk_bf16_f32 v22, v22, v23
	v_cvt_pk_bf16_f32 v23, v24, v25
	ds_write_b64 v228, v[34:35] offset:59136
	ds_write_b64 v228, v[30:31] offset:59168
	ds_write_b64 v228, v[26:27] offset:59200
	ds_write_b64 v228, v[22:23] offset:59232
	s_ashr_i32 s43, s42, 31
	v_mov_b32_e32 v34, v175
	s_lshl_b64 s[12:13], s[42:43], 1
	s_waitcnt lgkmcnt(0)
	s_barrier
; #define RTID opaque_tid()
; __device__ __forceinline__ void phase_gemm_f32(const u16* A, const u16* Bt, int K, u16* out, u16* smem,
;                                                volatile LAS unsigned* vb_) {
;     ...
;     const int tid2 = RTID;
; #pragma unroll
;     for (int k = 0; k < 16; ++k) {
;       const int c = tid2 + 512 * k;
;       const int row = c >> 5, ch = c & 31;
;       const uint4 v = *(const uint4*)(smem + row * 264 + ch * 8);
;       *(uint4*)(out + (size_t)(mt * 256 + row) * 1024 + nt * 256 + ch * 8) = v;
;     }
;     __syncthreads();
	s_add_u32 s12, s11, s12
	v_lshlrev_b32_e32 v0, 4, v34
	v_and_b32_e32 v0, 0x1f0, v0
	s_addc_u32 s13, s20, s13
	v_ashrrev_i32_e32 v26, 5, v34
	v_lshl_add_u64 v[30:31], s[12:13], 0, v[0:1]
	v_mad_u64_u32 v[22:23], s[12:13], v26, s2, v[0:1]
	v_add_u32_e32 v26, s23, v26
	v_ashrrev_i32_e32 v27, 31, v26
	ds_read_b128 v[22:25], v22
	v_lshlrev_b64 v[26:27], 11, v[26:27]
	v_lshl_add_u64 v[32:33], v[30:31], 0, v[26:27]
	v_add_u32_e32 v26, 0x200, v34
	v_ashrrev_i32_e32 v35, 5, v26
	v_mad_u64_u32 v[26:27], s[12:13], v35, s2, v[0:1]
	ds_read_b128 v[26:29], v26
	s_waitcnt lgkmcnt(1)
	global_store_dwordx4 v[32:33], v[22:25], off
	s_and_b64 vcc, exec, s[40:41]
	s_mov_b32 s37, s36
	v_add_u32_e32 v22, s23, v35
	v_ashrrev_i32_e32 v23, 31, v22
	v_lshlrev_b64 v[22:23], 11, v[22:23]
	v_lshl_add_u64 v[22:23], v[30:31], 0, v[22:23]
	s_waitcnt lgkmcnt(0)
	global_store_dwordx4 v[22:23], v[26:29], off
	v_add_u32_e32 v22, 0x400, v34
	s_nop 0
	v_ashrrev_i32_e32 v26, 5, v22
	v_mad_u64_u32 v[22:23], s[12:13], v26, s2, v[0:1]
	v_add_u32_e32 v26, s23, v26
	v_ashrrev_i32_e32 v27, 31, v26
	ds_read_b128 v[22:25], v22
	v_lshlrev_b64 v[26:27], 11, v[26:27]
	v_lshl_add_u64 v[32:33], v[30:31], 0, v[26:27]
	v_add_u32_e32 v26, 0x600, v34
	v_ashrrev_i32_e32 v35, 5, v26
	v_mad_u64_u32 v[26:27], s[12:13], v35, s2, v[0:1]
	ds_read_b128 v[26:29], v26
	s_waitcnt lgkmcnt(1)
	global_store_dwordx4 v[32:33], v[22:25], off
	s_nop 1
	v_add_u32_e32 v22, s23, v35
	v_ashrrev_i32_e32 v23, 31, v22
	v_lshlrev_b64 v[22:23], 11, v[22:23]
	v_lshl_add_u64 v[22:23], v[30:31], 0, v[22:23]
	s_waitcnt lgkmcnt(0)
	global_store_dwordx4 v[22:23], v[26:29], off
	v_add_u32_e32 v22, 0x800, v34
	s_nop 0
	v_ashrrev_i32_e32 v26, 5, v22
	v_mad_u64_u32 v[22:23], s[12:13], v26, s2, v[0:1]
	v_add_u32_e32 v26, s23, v26
	v_ashrrev_i32_e32 v27, 31, v26
	ds_read_b128 v[22:25], v22
	v_lshlrev_b64 v[26:27], 11, v[26:27]
	v_lshl_add_u64 v[32:33], v[30:31], 0, v[26:27]
	v_add_u32_e32 v26, 0xa00, v34
	v_ashrrev_i32_e32 v35, 5, v26
	v_mad_u64_u32 v[26:27], s[12:13], v35, s2, v[0:1]
	ds_read_b128 v[26:29], v26
	s_waitcnt lgkmcnt(1)
	global_store_dwordx4 v[32:33], v[22:25], off
	s_nop 1
	v_add_u32_e32 v22, s23, v35
	v_ashrrev_i32_e32 v23, 31, v22
	v_lshlrev_b64 v[22:23], 11, v[22:23]
	v_lshl_add_u64 v[22:23], v[30:31], 0, v[22:23]
	s_waitcnt lgkmcnt(0)
	global_store_dwordx4 v[22:23], v[26:29], off
	v_add_u32_e32 v22, 0xc00, v34
	s_nop 0
	v_ashrrev_i32_e32 v26, 5, v22
	v_mad_u64_u32 v[22:23], s[12:13], v26, s2, v[0:1]
	v_add_u32_e32 v26, s23, v26
	v_ashrrev_i32_e32 v27, 31, v26
	ds_read_b128 v[22:25], v22
	v_lshlrev_b64 v[26:27], 11, v[26:27]
	v_lshl_add_u64 v[32:33], v[30:31], 0, v[26:27]
	v_add_u32_e32 v26, 0xe00, v34
	v_ashrrev_i32_e32 v35, 5, v26
	v_mad_u64_u32 v[26:27], s[12:13], v35, s2, v[0:1]
	ds_read_b128 v[26:29], v26
	s_waitcnt lgkmcnt(1)
	global_store_dwordx4 v[32:33], v[22:25], off
	s_nop 1
	v_add_u32_e32 v22, s23, v35
	v_ashrrev_i32_e32 v23, 31, v22
	v_lshlrev_b64 v[22:23], 11, v[22:23]
	v_lshl_add_u64 v[22:23], v[30:31], 0, v[22:23]
	s_waitcnt lgkmcnt(0)
	global_store_dwordx4 v[22:23], v[26:29], off
	v_add_u32_e32 v22, 0x1000, v34
	s_nop 0
	v_ashrrev_i32_e32 v26, 5, v22
	v_mad_u64_u32 v[22:23], s[12:13], v26, s2, v[0:1]
	v_add_u32_e32 v26, s23, v26
	v_ashrrev_i32_e32 v27, 31, v26
	ds_read_b128 v[22:25], v22
	v_lshlrev_b64 v[26:27], 11, v[26:27]
	v_lshl_add_u64 v[32:33], v[30:31], 0, v[26:27]
	v_add_u32_e32 v26, 0x1200, v34
	v_ashrrev_i32_e32 v35, 5, v26
	v_mad_u64_u32 v[26:27], s[12:13], v35, s2, v[0:1]
	ds_read_b128 v[26:29], v26
	s_waitcnt lgkmcnt(1)
	global_store_dwordx4 v[32:33], v[22:25], off
	s_nop 1
	v_add_u32_e32 v22, s23, v35
	v_ashrrev_i32_e32 v23, 31, v22
	v_lshlrev_b64 v[22:23], 11, v[22:23]
	v_lshl_add_u64 v[22:23], v[30:31], 0, v[22:23]
	s_waitcnt lgkmcnt(0)
	global_store_dwordx4 v[22:23], v[26:29], off
	v_add_u32_e32 v22, 0x1400, v34
	s_nop 0
	v_ashrrev_i32_e32 v26, 5, v22
	v_mad_u64_u32 v[22:23], s[12:13], v26, s2, v[0:1]
	v_add_u32_e32 v26, s23, v26
	v_ashrrev_i32_e32 v27, 31, v26
	ds_read_b128 v[22:25], v22
	v_lshlrev_b64 v[26:27], 11, v[26:27]
	v_lshl_add_u64 v[32:33], v[30:31], 0, v[26:27]
	v_add_u32_e32 v26, 0x1600, v34
	v_ashrrev_i32_e32 v35, 5, v26
	v_mad_u64_u32 v[26:27], s[12:13], v35, s2, v[0:1]
	ds_read_b128 v[26:29], v26
	s_waitcnt lgkmcnt(1)
	global_store_dwordx4 v[32:33], v[22:25], off
	s_nop 1
	v_add_u32_e32 v22, s23, v35
	v_ashrrev_i32_e32 v23, 31, v22
	v_lshlrev_b64 v[22:23], 11, v[22:23]
	v_lshl_add_u64 v[22:23], v[30:31], 0, v[22:23]
	s_waitcnt lgkmcnt(0)
	global_store_dwordx4 v[22:23], v[26:29], off
	v_add_u32_e32 v22, 0x1800, v34
	s_nop 0
	v_ashrrev_i32_e32 v26, 5, v22
	v_mad_u64_u32 v[22:23], s[12:13], v26, s2, v[0:1]
	v_add_u32_e32 v26, s23, v26
	v_ashrrev_i32_e32 v27, 31, v26
	ds_read_b128 v[22:25], v22
	v_lshlrev_b64 v[26:27], 11, v[26:27]
	v_lshl_add_u64 v[32:33], v[30:31], 0, v[26:27]
	v_add_u32_e32 v26, 0x1a00, v34
	v_ashrrev_i32_e32 v35, 5, v26
	v_mad_u64_u32 v[26:27], s[12:13], v35, s2, v[0:1]
	ds_read_b128 v[26:29], v26
	s_waitcnt lgkmcnt(1)
	global_store_dwordx4 v[32:33], v[22:25], off
	s_nop 1
	v_add_u32_e32 v22, s23, v35
	v_ashrrev_i32_e32 v23, 31, v22
	v_lshlrev_b64 v[22:23], 11, v[22:23]
	v_lshl_add_u64 v[22:23], v[30:31], 0, v[22:23]
	s_waitcnt lgkmcnt(0)
	global_store_dwordx4 v[22:23], v[26:29], off
	v_add_u32_e32 v22, 0x1c00, v34
	s_nop 0
	v_ashrrev_i32_e32 v26, 5, v22
	v_mad_u64_u32 v[22:23], s[12:13], v26, s2, v[0:1]
	v_add_u32_e32 v26, s23, v26
	v_ashrrev_i32_e32 v27, 31, v26
	ds_read_b128 v[22:25], v22
	v_lshlrev_b64 v[26:27], 11, v[26:27]
	v_lshl_add_u64 v[32:33], v[30:31], 0, v[26:27]
	v_add_u32_e32 v26, 0x1e00, v34
	v_ashrrev_i32_e32 v34, 5, v26
	v_mad_u64_u32 v[26:27], s[12:13], v34, s2, v[0:1]
	ds_read_b128 v[26:29], v26
	s_waitcnt lgkmcnt(1)
	global_store_dwordx4 v[32:33], v[22:25], off
	s_mov_b64 s[12:13], -1
	s_nop 0
	v_add_u32_e32 v22, s23, v34
	v_ashrrev_i32_e32 v23, 31, v22
	v_lshlrev_b64 v[22:23], 11, v[22:23]
	v_lshl_add_u64 v[22:23], v[30:31], 0, v[22:23]
	s_waitcnt lgkmcnt(0)
	global_store_dwordx4 v[22:23], v[26:29], off
	s_barrier
	s_cbranch_vccz .LBB0_478

; template <int MI, int NJ> ...
;     ...
;   for (int kt = 0; kt < nk; ++kt) {
;     const int buf = kt & 1;
;     {
;       G8STORE(buf ^ 1);
;       const u16* ga_ = (kt + 2 < nk) ? Ag + (kt + 2) * 64 : Ag + nAoff;
;       const u16* gb_ = (kt + 2 < nk) ? Bg + (kt + 2) * 64 : Bg + nBoff;
;       G8LOADP(ga_, gb_);
;     }
;     __builtin_amdgcn_sched_barrier(0);
;     __builtin_amdgcn_s_setprio(1);
;     const u16* a = ra_ + buf * AROWS * 64;
;     const u16* b = rb_ + buf * BROWS * 64;
; #pragma unroll
;     for (int ks = 0; ks < 2; ++ks) {
;       const u16* a_ = ks ? a + dsw : a;
;       const u16* b_ = ks ? b + dsw : b;
;       bf16x8 bfr[NJ];
; #pragma unroll
;       for (int j = 0; j < NJ; ++j) bfr[j] = *(const bf16x8*)(b_ + j * 16 * 64);
; #pragma unroll
;       for (int ih = 0; ih < MI / 4; ++ih) {
;         bf16x8 af[4];
; #pragma unroll
;         for (int i = 0; i < 4; ++i) af[i] = *(const bf16x8*)(a_ + (ih * 4 + i) * 16 * 64);
; #pragma unroll
;         for (int i = 0; i < 4; ++i)
; #pragma unroll
;           for (int j = 0; j < NJ; ++j) acc[ih * 4 + i][j] = mfma16(af[i], bfr[j], acc[ih * 4 + i][j]);
;       }
;     }
;     __builtin_amdgcn_s_setprio(0);
;     __builtin_amdgcn_sched_barrier(0);
;     __syncthreads();
;   }
.LBB0_601:
	s_setprio 1
	s_waitcnt lgkmcnt(6)
	v_mfma_f32_16x16x32_bf16 v[158:161], v[212:215], v[208:211], v[158:161]
	s_waitcnt lgkmcnt(5)
	v_mfma_f32_16x16x32_bf16 v[154:157], v[216:219], v[208:211], v[154:157]
	s_waitcnt lgkmcnt(4)
	v_mfma_f32_16x16x32_bf16 v[150:153], v[220:223], v[208:211], v[150:153]
	s_waitcnt lgkmcnt(3)
	v_mfma_f32_16x16x32_bf16 v[146:149], v[224:227], v[208:211], v[146:149]
	ds_read_b128 v[208:211], v228 offset:8192
	s_waitcnt lgkmcnt(3)
	v_mfma_f32_16x16x32_bf16 v[142:145], v[212:215], v[234:237], v[142:145]
	v_mfma_f32_16x16x32_bf16 v[138:141], v[216:219], v[234:237], v[138:141]
	v_mfma_f32_16x16x32_bf16 v[134:137], v[220:223], v[234:237], v[134:137]
	v_mfma_f32_16x16x32_bf16 v[130:133], v[224:227], v[234:237], v[130:133]
	ds_read_b128 v[234:237], v228 offset:10240
	s_waitcnt lgkmcnt(3)
	v_mfma_f32_16x16x32_bf16 v[126:129], v[212:215], v[238:241], v[126:129]
	v_mfma_f32_16x16x32_bf16 v[122:125], v[216:219], v[238:241], v[122:125]
	v_mfma_f32_16x16x32_bf16 v[118:121], v[220:223], v[238:241], v[118:121]
	v_mfma_f32_16x16x32_bf16 v[114:117], v[224:227], v[238:241], v[114:117]
	ds_read_b128 v[238:241], v228 offset:12288
	ds_read_b128 v[242:245], v229
	ds_read_b128 v[246:249], v229 offset:2048
	s_waitcnt lgkmcnt(5)
	v_mfma_f32_16x16x32_bf16 v[110:113], v[212:215], v[204:207], v[110:113]
	v_mfma_f32_16x16x32_bf16 v[106:109], v[216:219], v[204:207], v[106:109]
	v_mfma_f32_16x16x32_bf16 v[102:105], v[220:223], v[204:207], v[102:105]
	v_mfma_f32_16x16x32_bf16 v[98:101], v[224:227], v[204:207], v[98:101]
	ds_read_b128 v[204:207], v228 offset:14336
	ds_read_b128 v[190:193], v229 offset:4096
	ds_read_b128 v[170:173], v229 offset:6144
	s_waitcnt lgkmcnt(7)
	v_mfma_f32_16x16x32_bf16 v[94:97], v[212:215], v[208:211], v[94:97]
	v_mfma_f32_16x16x32_bf16 v[90:93], v[216:219], v[208:211], v[90:93]
	v_mfma_f32_16x16x32_bf16 v[86:89], v[220:223], v[208:211], v[86:89]
	v_mfma_f32_16x16x32_bf16 v[82:85], v[224:227], v[208:211], v[82:85]
	v_add_u32_e32 v228, v228, v196
	ds_read_b128 v[208:211], v228
	s_waitcnt vmcnt(7)
	ds_write_b128 v199, v[2:5]
	global_load_dwordx4 v[2:5], v169, s[50:51]
	s_waitcnt lgkmcnt(8)
	v_mfma_f32_16x16x32_bf16 v[78:81], v[212:215], v[234:237], v[78:81]
	v_mfma_f32_16x16x32_bf16 v[74:77], v[216:219], v[234:237], v[74:77]
	v_mfma_f32_16x16x32_bf16 v[70:73], v[220:223], v[234:237], v[70:73]
	v_mfma_f32_16x16x32_bf16 v[66:69], v[224:227], v[234:237], v[66:69]
	ds_read_b128 v[234:237], v228 offset:2048
	s_waitcnt vmcnt(7)
	ds_write_b128 v199, v[6:9] offset:8192
	global_load_dwordx4 v[6:9], v194, s[50:51]
	s_waitcnt lgkmcnt(9)
	v_mfma_f32_16x16x32_bf16 v[62:65], v[212:215], v[238:241], v[62:65]
	v_mfma_f32_16x16x32_bf16 v[58:61], v[216:219], v[238:241], v[58:61]
	v_mfma_f32_16x16x32_bf16 v[54:57], v[220:223], v[238:241], v[54:57]
	v_mfma_f32_16x16x32_bf16 v[50:53], v[224:227], v[238:241], v[50:53]
	ds_read_b128 v[238:241], v228 offset:4096
	s_waitcnt vmcnt(7)
	ds_write_b128 v199, v[10:13] offset:16384
	global_load_dwordx4 v[10:13], v195, s[50:51]
	s_waitcnt lgkmcnt(8)
	v_mfma_f32_16x16x32_bf16 v[46:49], v[212:215], v[204:207], v[46:49]
	v_mfma_f32_16x16x32_bf16 v[42:45], v[216:219], v[204:207], v[42:45]
	v_mfma_f32_16x16x32_bf16 v[38:41], v[220:223], v[204:207], v[38:41]
	v_mfma_f32_16x16x32_bf16 v[34:37], v[224:227], v[204:207], v[34:37]
	ds_read_b128 v[204:207], v228 offset:6144
	s_waitcnt vmcnt(7)
	ds_write_b128 v199, v[18:21] offset:24576
	global_load_dwordx4 v[18:21], v198, s[50:51]
	s_waitcnt lgkmcnt(7)
	v_mfma_f32_16x16x32_bf16 v[158:161], v[242:245], v[208:211], v[158:161]
	v_mfma_f32_16x16x32_bf16 v[154:157], v[246:249], v[208:211], v[154:157]
	v_mfma_f32_16x16x32_bf16 v[150:153], v[190:193], v[208:211], v[150:153]
	v_mfma_f32_16x16x32_bf16 v[146:149], v[170:173], v[208:211], v[146:149]
	ds_read_b128 v[208:211], v228 offset:8192
	s_waitcnt vmcnt(7)
	ds_write_b128 v200, v[14:17]
	global_load_dwordx4 v[14:17], v169, s[52:53]
	s_waitcnt lgkmcnt(7)
	v_mfma_f32_16x16x32_bf16 v[142:145], v[242:245], v[234:237], v[142:145]
	v_mfma_f32_16x16x32_bf16 v[138:141], v[246:249], v[234:237], v[138:141]
	v_mfma_f32_16x16x32_bf16 v[134:137], v[190:193], v[234:237], v[134:137]
	v_mfma_f32_16x16x32_bf16 v[130:133], v[170:173], v[234:237], v[130:133]
	ds_read_b128 v[234:237], v228 offset:10240
	s_waitcnt vmcnt(7)
	ds_write_b128 v200, v[22:25] offset:8192
	global_load_dwordx4 v[22:25], v194, s[52:53]
	s_waitcnt lgkmcnt(7)
	v_mfma_f32_16x16x32_bf16 v[126:129], v[242:245], v[238:241], v[126:129]
	v_mfma_f32_16x16x32_bf16 v[122:125], v[246:249], v[238:241], v[122:125]
	v_mfma_f32_16x16x32_bf16 v[118:121], v[190:193], v[238:241], v[118:121]
	v_mfma_f32_16x16x32_bf16 v[114:117], v[170:173], v[238:241], v[114:117]
	ds_read_b128 v[238:241], v228 offset:12288
	s_waitcnt vmcnt(7)
	ds_write_b128 v200, v[26:29] offset:16384
	global_load_dwordx4 v[26:29], v195, s[52:53]
	s_waitcnt lgkmcnt(7)
	v_mfma_f32_16x16x32_bf16 v[110:113], v[242:245], v[204:207], v[110:113]
	v_mfma_f32_16x16x32_bf16 v[106:109], v[246:249], v[204:207], v[106:109]
	v_mfma_f32_16x16x32_bf16 v[102:105], v[190:193], v[204:207], v[102:105]
	v_mfma_f32_16x16x32_bf16 v[98:101], v[170:173], v[204:207], v[98:101]
	ds_read_b128 v[204:207], v228 offset:14336
	s_waitcnt vmcnt(7)
	ds_write_b128 v200, v[30:33] offset:24576
	global_load_dwordx4 v[30:33], v198, s[52:53]
	s_waitcnt lgkmcnt(7)
	v_mfma_f32_16x16x32_bf16 v[94:97], v[242:245], v[208:211], v[94:97]
	v_mfma_f32_16x16x32_bf16 v[90:93], v[246:249], v[208:211], v[90:93]
	v_mfma_f32_16x16x32_bf16 v[86:89], v[190:193], v[208:211], v[86:89]
	v_mfma_f32_16x16x32_bf16 v[82:85], v[170:173], v[208:211], v[82:85]
	s_waitcnt lgkmcnt(0)
	s_setprio 0
	s_barrier
; __device__ __forceinline__ float siluf_(float x) { return x / (1.0f + __expf(-x)); }
; template <int MI, int NJ> ...
;     ...
;     const u16* a = ra_ + buf * AROWS * 64;
;     const u16* b = rb_ + buf * BROWS * 64;
; #pragma unroll
;     for (int ks = 0; ks < 2; ++ks) {
;       const u16* a_ = ks ? a + dsw : a;
;       const u16* b_ = ks ? b + dsw : b;
;       bf16x8 bfr[NJ];
; #pragma unroll
;       for (int j = 0; j < NJ; ++j) bfr[j] = *(const bf16x8*)(b_ + j * 16 * 64);
; #pragma unroll
;       for (int ih = 0; ih < MI / 4; ++ih) {
;         bf16x8 af[4];
; #pragma unroll
;         for (int i = 0; i < 4; ++i) af[i] = *(const bf16x8*)(a_ + (ih * 4 + i) * 16 * 64);
; #pragma unroll
;         for (int i = 0; i < 4; ++i)
; #pragma unroll
;           for (int j = 0; j < NJ; ++j) acc[ih * 4 + i][j] = mfma16(af[i], bfr[j], acc[ih * 4 + i][j]);
;       }
;     }
; __device__ __forceinline__ void phase_ffn_up(const Params& p, const u16* Wgu, u16* smem, volatile LAS unsigned* vb_) {
;     ...
; #pragma unroll
;     for (int i = 0; i < 8; ++i)
; #pragma unroll
;       for (int jp = 0; jp < 2; ++jp) {
; #pragma unroll
;         for (int r = 0; r < 4; ++r) {
;           const float g = acc[i][2 * jp][r], u = acc[i][2 * jp + 1][r];
;           smem[(wm * 128 + i * 16 + (lane >> 4) * 4 + r) * 136 + (wn * 2 + jp) * 16 + (lane & 15)] = f2bf(siluf_(g) * u);
;         }
;         __builtin_amdgcn_sched_barrier(0);
;       }
	s_add_i32 s43, s43, 1
	s_add_u32 s22, s22, 64
	s_addc_u32 s23, s23, 0
	s_addk_i32 s42, 0x4000
	s_and_b32 s48, s42, 0x4000
	s_xor_b32 s44, s48, 0x4000
	s_lshl_b32 s44, s44, 1
	v_add_u32_e32 v199, s44, v185
	v_add_u32_e32 v200, s44, v186
	s_cmp_lt_u32 s43, 14
	s_cselect_b32 s45, s23, s13
	s_cselect_b32 s44, s22, s12
	s_cselect_b32 s47, s23, s21
	s_cselect_b32 s46, s22, s20
	s_lshl_b64 s[44:45], s[44:45], 1
	s_lshl_b64 s[46:47], s[46:47], 1
	s_add_u32 s50, s62, s44
	s_addc_u32 s51, s63, s45
	s_add_u32 s52, s64, s46
	s_addc_u32 s53, s65, s47
	s_lshl_b32 s44, s48, 1
	v_add_u32_e32 v228, s44, v187
	v_add_u32_e32 v229, s44, v188
	s_setprio 1
	ds_read_b128 v[212:215], v229
	ds_read_b128 v[208:211], v228
	ds_read_b128 v[216:219], v229 offset:2048
	ds_read_b128 v[220:223], v229 offset:4096
	ds_read_b128 v[224:227], v229 offset:6144
	v_mfma_f32_16x16x32_bf16 v[78:81], v[242:245], v[234:237], v[78:81]
	v_mfma_f32_16x16x32_bf16 v[74:77], v[246:249], v[234:237], v[74:77]
	v_mfma_f32_16x16x32_bf16 v[70:73], v[190:193], v[234:237], v[70:73]
	v_mfma_f32_16x16x32_bf16 v[66:69], v[170:173], v[234:237], v[66:69]
	ds_read_b128 v[234:237], v228 offset:2048
	v_mfma_f32_16x16x32_bf16 v[62:65], v[242:245], v[238:241], v[62:65]
	v_mfma_f32_16x16x32_bf16 v[58:61], v[246:249], v[238:241], v[58:61]
	v_mfma_f32_16x16x32_bf16 v[54:57], v[190:193], v[238:241], v[54:57]
	v_mfma_f32_16x16x32_bf16 v[50:53], v[170:173], v[238:241], v[50:53]
	ds_read_b128 v[238:241], v228 offset:4096
	v_mfma_f32_16x16x32_bf16 v[46:49], v[242:245], v[204:207], v[46:49]
	v_mfma_f32_16x16x32_bf16 v[42:45], v[246:249], v[204:207], v[42:45]
	v_mfma_f32_16x16x32_bf16 v[38:41], v[190:193], v[204:207], v[38:41]
	v_mfma_f32_16x16x32_bf16 v[34:37], v[170:173], v[204:207], v[34:37]
	ds_read_b128 v[204:207], v228 offset:6144
	v_add_u32_e32 v229, v229, v196
	s_setprio 0
	s_cmpk_lg_i32 s22, 0x480
	s_cbranch_scc1 .LBB0_601
	v_and_b32_e32 v228, 15, v175
	v_bfe_u32 v229, v175, 8, 1
	v_lshl_or_b32 v228, v229, 7, v228
	v_mul_u32_u24_e32 v228, 0x110, v228
	v_bfe_u32 v229, v175, 6, 2
	v_lshl_add_u32 v228, v229, 6, v228
	v_bfe_u32 v229, v175, 4, 2
	v_lshl_add_u32 v228, v229, 3, v228
	v_mul_f32_e32 v208, 0xbfb8aa3b, v158
	v_mul_f32_e32 v209, 0xbfb8aa3b, v159
	v_mul_f32_e32 v210, 0xbfb8aa3b, v160
	v_mul_f32_e32 v211, 0xbfb8aa3b, v161
	v_mul_f32_e32 v212, 0xbfb8aa3b, v150
	v_mul_f32_e32 v213, 0xbfb8aa3b, v151
	v_mul_f32_e32 v214, 0xbfb8aa3b, v152
	v_mul_f32_e32 v215, 0xbfb8aa3b, v153
	v_min_f32_e32 v208, 0x42fc0000, v208
	v_min_f32_e32 v209, 0x42fc0000, v209
	v_min_f32_e32 v210, 0x42fc0000, v210
	v_min_f32_e32 v211, 0x42fc0000, v211
	v_min_f32_e32 v212, 0x42fc0000, v212
	v_min_f32_e32 v213, 0x42fc0000, v213
	v_min_f32_e32 v214, 0x42fc0000, v214
	v_min_f32_e32 v215, 0x42fc0000, v215
	v_exp_f32_e32 v208, v208
	v_exp_f32_e32 v209, v209
	v_exp_f32_e32 v210, v210
	v_exp_f32_e32 v211, v211
	v_exp_f32_e32 v212, v212
	v_exp_f32_e32 v213, v213
	v_exp_f32_e32 v214, v214
	v_exp_f32_e32 v215, v215
	v_add_f32_e32 v208, 1.0, v208
	v_add_f32_e32 v209, 1.0, v209
	v_add_f32_e32 v210, 1.0, v210
	v_add_f32_e32 v211, 1.0, v211
	v_add_f32_e32 v212, 1.0, v212
	v_add_f32_e32 v213, 1.0, v213
	v_add_f32_e32 v214, 1.0, v214
	v_add_f32_e32 v215, 1.0, v215
	v_rcp_f32_e32 v216, v208
	v_rcp_f32_e32 v217, v209
	v_rcp_f32_e32 v218, v210
	v_rcp_f32_e32 v219, v211
	v_rcp_f32_e32 v220, v212
	v_rcp_f32_e32 v221, v213
	v_rcp_f32_e32 v222, v214
	v_rcp_f32_e32 v223, v215
	v_fma_f32 v208, -v208, v216, 1.0
	v_fma_f32 v209, -v209, v217, 1.0
	v_fma_f32 v210, -v210, v218, 1.0
	v_fma_f32 v211, -v211, v219, 1.0
	v_fma_f32 v212, -v212, v220, 1.0
	v_fma_f32 v213, -v213, v221, 1.0
	v_fma_f32 v214, -v214, v222, 1.0
	v_fma_f32 v215, -v215, v223, 1.0
	v_fmac_f32_e32 v216, v208, v216
	v_fmac_f32_e32 v217, v209, v217
	v_fmac_f32_e32 v218, v210, v218
	v_fmac_f32_e32 v219, v211, v219
	v_fmac_f32_e32 v220, v212, v220
	v_fmac_f32_e32 v221, v213, v221
	v_fmac_f32_e32 v222, v214, v222
	v_fmac_f32_e32 v223, v215, v223
	v_mul_f32_e32 v158, v158, v216
	v_mul_f32_e32 v159, v159, v217
	v_mul_f32_e32 v160, v160, v218
	v_mul_f32_e32 v161, v161, v219
	v_mul_f32_e32 v150, v150, v220
	v_mul_f32_e32 v151, v151, v221
	v_mul_f32_e32 v152, v152, v222
	v_mul_f32_e32 v153, v153, v223
	v_mul_f32_e32 v158, v158, v154
	v_mul_f32_e32 v159, v159, v155
	v_mul_f32_e32 v160, v160, v156
	v_mul_f32_e32 v161, v161, v157
	v_mul_f32_e32 v150, v150, v146
	v_mul_f32_e32 v151, v151, v147
	v_mul_f32_e32 v152, v152, v148
	v_mul_f32_e32 v153, v153, v149
	v_cvt_pk_bf16_f32 v158, v158, v159
	v_cvt_pk_bf16_f32 v159, v160, v161
	v_cvt_pk_bf16_f32 v150, v150, v151
	v_cvt_pk_bf16_f32 v151, v152, v153
	ds_write_b64 v228, v[158:159]
	ds_write_b64 v228, v[150:151] offset:32
	v_mul_f32_e32 v208, 0xbfb8aa3b, v142
	v_mul_f32_e32 v209, 0xbfb8aa3b, v143
	v_mul_f32_e32 v210, 0xbfb8aa3b, v144
	v_mul_f32_e32 v211, 0xbfb8aa3b, v145
	v_mul_f32_e32 v212, 0xbfb8aa3b, v134
	v_mul_f32_e32 v213, 0xbfb8aa3b, v135
	v_mul_f32_e32 v214, 0xbfb8aa3b, v136
	v_mul_f32_e32 v215, 0xbfb8aa3b, v137
	v_min_f32_e32 v208, 0x42fc0000, v208
	v_min_f32_e32 v209, 0x42fc0000, v209
	v_min_f32_e32 v210, 0x42fc0000, v210
	v_min_f32_e32 v211, 0x42fc0000, v211
	v_min_f32_e32 v212, 0x42fc0000, v212
	v_min_f32_e32 v213, 0x42fc0000, v213
	v_min_f32_e32 v214, 0x42fc0000, v214
	v_min_f32_e32 v215, 0x42fc0000, v215
	v_exp_f32_e32 v208, v208
	v_exp_f32_e32 v209, v209
	v_exp_f32_e32 v210, v210
	v_exp_f32_e32 v211, v211
	v_exp_f32_e32 v212, v212
	v_exp_f32_e32 v213, v213
	v_exp_f32_e32 v214, v214
	v_exp_f32_e32 v215, v215
	v_add_f32_e32 v208, 1.0, v208
	v_add_f32_e32 v209, 1.0, v209
	v_add_f32_e32 v210, 1.0, v210
	v_add_f32_e32 v211, 1.0, v211
	v_add_f32_e32 v212, 1.0, v212
; __device__ __forceinline__ float siluf_(float x) { return x / (1.0f + __expf(-x)); }
; __device__ __forceinline__ void phase_ffn_up(const Params& p, const u16* Wgu, u16* smem, volatile LAS unsigned* vb_) {
;     ...
; #pragma unroll
;     for (int i = 0; i < 8; ++i)
; #pragma unroll
;       for (int jp = 0; jp < 2; ++jp) {
; #pragma unroll
;         for (int r = 0; r < 4; ++r) {
;           const float g = acc[i][2 * jp][r], u = acc[i][2 * jp + 1][r];
;           smem[(wm * 128 + i * 16 + (lane >> 4) * 4 + r) * 136 + (wn * 2 + jp) * 16 + (lane & 15)] = f2bf(siluf_(g) * u);
;         }
;         __builtin_amdgcn_sched_barrier(0);
;       }
	v_add_f32_e32 v213, 1.0, v213
	v_add_f32_e32 v214, 1.0, v214
	v_add_f32_e32 v215, 1.0, v215
	v_rcp_f32_e32 v216, v208
	v_rcp_f32_e32 v217, v209
	v_rcp_f32_e32 v218, v210
	v_rcp_f32_e32 v219, v211
	v_rcp_f32_e32 v220, v212
	v_rcp_f32_e32 v221, v213
	v_rcp_f32_e32 v222, v214
	v_rcp_f32_e32 v223, v215
	v_fma_f32 v208, -v208, v216, 1.0
	v_fma_f32 v209, -v209, v217, 1.0
	v_fma_f32 v210, -v210, v218, 1.0
	v_fma_f32 v211, -v211, v219, 1.0
	v_fma_f32 v212, -v212, v220, 1.0
	v_fma_f32 v213, -v213, v221, 1.0
	v_fma_f32 v214, -v214, v222, 1.0
	v_fma_f32 v215, -v215, v223, 1.0
	v_fmac_f32_e32 v216, v208, v216
	v_fmac_f32_e32 v217, v209, v217
	v_fmac_f32_e32 v218, v210, v218
	v_fmac_f32_e32 v219, v211, v219
	v_fmac_f32_e32 v220, v212, v220
	v_fmac_f32_e32 v221, v213, v221
	v_fmac_f32_e32 v222, v214, v222
	v_fmac_f32_e32 v223, v215, v223
	v_mul_f32_e32 v142, v142, v216
	v_mul_f32_e32 v143, v143, v217
	v_mul_f32_e32 v144, v144, v218
	v_mul_f32_e32 v145, v145, v219
	v_mul_f32_e32 v134, v134, v220
	v_mul_f32_e32 v135, v135, v221
	v_mul_f32_e32 v136, v136, v222
	v_mul_f32_e32 v137, v137, v223
	v_mul_f32_e32 v142, v142, v138
	v_mul_f32_e32 v143, v143, v139
	v_mul_f32_e32 v144, v144, v140
	v_mul_f32_e32 v145, v145, v141
	v_mul_f32_e32 v134, v134, v130
	v_mul_f32_e32 v135, v135, v131
	v_mul_f32_e32 v136, v136, v132
	v_mul_f32_e32 v137, v137, v133
	v_cvt_pk_bf16_f32 v142, v142, v143
	v_cvt_pk_bf16_f32 v143, v144, v145
	v_cvt_pk_bf16_f32 v134, v134, v135
	v_cvt_pk_bf16_f32 v135, v136, v137
	ds_write_b64 v228, v[142:143] offset:4352
	ds_write_b64 v228, v[134:135] offset:4384
	v_mul_f32_e32 v208, 0xbfb8aa3b, v126
	v_mul_f32_e32 v209, 0xbfb8aa3b, v127
	v_mul_f32_e32 v210, 0xbfb8aa3b, v128
	v_mul_f32_e32 v211, 0xbfb8aa3b, v129
	v_mul_f32_e32 v212, 0xbfb8aa3b, v118
	v_mul_f32_e32 v213, 0xbfb8aa3b, v119
	v_mul_f32_e32 v214, 0xbfb8aa3b, v120
	v_mul_f32_e32 v215, 0xbfb8aa3b, v121
	v_min_f32_e32 v208, 0x42fc0000, v208
	v_min_f32_e32 v209, 0x42fc0000, v209
	v_min_f32_e32 v210, 0x42fc0000, v210
	v_min_f32_e32 v211, 0x42fc0000, v211
	v_min_f32_e32 v212, 0x42fc0000, v212
	v_min_f32_e32 v213, 0x42fc0000, v213
	v_min_f32_e32 v214, 0x42fc0000, v214
	v_min_f32_e32 v215, 0x42fc0000, v215
	v_exp_f32_e32 v208, v208
	v_exp_f32_e32 v209, v209
	v_exp_f32_e32 v210, v210
	v_exp_f32_e32 v211, v211
	v_exp_f32_e32 v212, v212
	v_exp_f32_e32 v213, v213
	v_exp_f32_e32 v214, v214
	v_exp_f32_e32 v215, v215
	v_add_f32_e32 v208, 1.0, v208
	v_add_f32_e32 v209, 1.0, v209
	v_add_f32_e32 v210, 1.0, v210
	v_add_f32_e32 v211, 1.0, v211
	v_add_f32_e32 v212, 1.0, v212
	v_add_f32_e32 v213, 1.0, v213
	v_add_f32_e32 v214, 1.0, v214
	v_add_f32_e32 v215, 1.0, v215
	v_rcp_f32_e32 v216, v208
	v_rcp_f32_e32 v217, v209
	v_rcp_f32_e32 v218, v210
	v_rcp_f32_e32 v219, v211
	v_rcp_f32_e32 v220, v212
	v_rcp_f32_e32 v221, v213
	v_rcp_f32_e32 v222, v214
	v_rcp_f32_e32 v223, v215
	v_fma_f32 v208, -v208, v216, 1.0
	v_fma_f32 v209, -v209, v217, 1.0
	v_fma_f32 v210, -v210, v218, 1.0
	v_fma_f32 v211, -v211, v219, 1.0
	v_fma_f32 v212, -v212, v220, 1.0
	v_fma_f32 v213, -v213, v221, 1.0
	v_fma_f32 v214, -v214, v222, 1.0
	v_fma_f32 v215, -v215, v223, 1.0
	v_fmac_f32_e32 v216, v208, v216
	v_fmac_f32_e32 v217, v209, v217
	v_fmac_f32_e32 v218, v210, v218
	v_fmac_f32_e32 v219, v211, v219
	v_fmac_f32_e32 v220, v212, v220
	v_fmac_f32_e32 v221, v213, v221
	v_fmac_f32_e32 v222, v214, v222
	v_fmac_f32_e32 v223, v215, v223
	v_mul_f32_e32 v126, v126, v216
	v_mul_f32_e32 v127, v127, v217
	v_mul_f32_e32 v128, v128, v218
	v_mul_f32_e32 v129, v129, v219
	v_mul_f32_e32 v118, v118, v220
	v_mul_f32_e32 v119, v119, v221
	v_mul_f32_e32 v120, v120, v222
	v_mul_f32_e32 v121, v121, v223
	v_mul_f32_e32 v126, v126, v122
	v_mul_f32_e32 v127, v127, v123
	v_mul_f32_e32 v128, v128, v124
	v_mul_f32_e32 v129, v129, v125
	v_mul_f32_e32 v118, v118, v114
	v_mul_f32_e32 v119, v119, v115
	v_mul_f32_e32 v120, v120, v116
	v_mul_f32_e32 v121, v121, v117
	v_cvt_pk_bf16_f32 v126, v126, v127
	v_cvt_pk_bf16_f32 v127, v128, v129
	v_cvt_pk_bf16_f32 v118, v118, v119
	v_cvt_pk_bf16_f32 v119, v120, v121
	ds_write_b64 v228, v[126:127] offset:8704
	ds_write_b64 v228, v[118:119] offset:8736
	v_mul_f32_e32 v208, 0xbfb8aa3b, v110
	v_mul_f32_e32 v209, 0xbfb8aa3b, v111
	v_mul_f32_e32 v210, 0xbfb8aa3b, v112
	v_mul_f32_e32 v211, 0xbfb8aa3b, v113
	v_mul_f32_e32 v212, 0xbfb8aa3b, v102
	v_mul_f32_e32 v213, 0xbfb8aa3b, v103
	v_mul_f32_e32 v214, 0xbfb8aa3b, v104
	v_mul_f32_e32 v215, 0xbfb8aa3b, v105
	v_min_f32_e32 v208, 0x42fc0000, v208
	v_min_f32_e32 v209, 0x42fc0000, v209
	v_min_f32_e32 v210, 0x42fc0000, v210
	v_min_f32_e32 v211, 0x42fc0000, v211
	v_min_f32_e32 v212, 0x42fc0000, v212
	v_min_f32_e32 v213, 0x42fc0000, v213
	v_min_f32_e32 v214, 0x42fc0000, v214
	v_min_f32_e32 v215, 0x42fc0000, v215
	v_exp_f32_e32 v208, v208
	v_exp_f32_e32 v209, v209
	v_exp_f32_e32 v210, v210
	v_exp_f32_e32 v211, v211
	v_exp_f32_e32 v212, v212
	v_exp_f32_e32 v213, v213
	v_exp_f32_e32 v214, v214
	v_exp_f32_e32 v215, v215
	v_add_f32_e32 v208, 1.0, v208
	v_add_f32_e32 v209, 1.0, v209
	v_add_f32_e32 v210, 1.0, v210
	v_add_f32_e32 v211, 1.0, v211
	v_add_f32_e32 v212, 1.0, v212
	v_add_f32_e32 v213, 1.0, v213
	v_add_f32_e32 v214, 1.0, v214
	v_add_f32_e32 v215, 1.0, v215
	v_rcp_f32_e32 v216, v208
	v_rcp_f32_e32 v217, v209
	v_rcp_f32_e32 v218, v210
	v_rcp_f32_e32 v219, v211
	v_rcp_f32_e32 v220, v212
	v_rcp_f32_e32 v221, v213
	v_rcp_f32_e32 v222, v214
	v_rcp_f32_e32 v223, v215
	v_fma_f32 v208, -v208, v216, 1.0
	v_fma_f32 v209, -v209, v217, 1.0
	v_fma_f32 v210, -v210, v218, 1.0
	v_fma_f32 v211, -v211, v219, 1.0
	v_fma_f32 v212, -v212, v220, 1.0
	v_fma_f32 v213, -v213, v221, 1.0
	v_fma_f32 v214, -v214, v222, 1.0
; __device__ __forceinline__ float siluf_(float x) { return x / (1.0f + __expf(-x)); }
; __device__ __forceinline__ void phase_ffn_up(const Params& p, const u16* Wgu, u16* smem, volatile LAS unsigned* vb_) {
;     ...
; #pragma unroll
;     for (int i = 0; i < 8; ++i)
; #pragma unroll
;       for (int jp = 0; jp < 2; ++jp) {
; #pragma unroll
;         for (int r = 0; r < 4; ++r) {
;           const float g = acc[i][2 * jp][r], u = acc[i][2 * jp + 1][r];
;           smem[(wm * 128 + i * 16 + (lane >> 4) * 4 + r) * 136 + (wn * 2 + jp) * 16 + (lane & 15)] = f2bf(siluf_(g) * u);
;         }
;         __builtin_amdgcn_sched_barrier(0);
;       }
	v_fma_f32 v215, -v215, v223, 1.0
	v_fmac_f32_e32 v216, v208, v216
	v_fmac_f32_e32 v217, v209, v217
	v_fmac_f32_e32 v218, v210, v218
	v_fmac_f32_e32 v219, v211, v219
	v_fmac_f32_e32 v220, v212, v220
	v_fmac_f32_e32 v221, v213, v221
	v_fmac_f32_e32 v222, v214, v222
	v_fmac_f32_e32 v223, v215, v223
	v_mul_f32_e32 v110, v110, v216
	v_mul_f32_e32 v111, v111, v217
	v_mul_f32_e32 v112, v112, v218
	v_mul_f32_e32 v113, v113, v219
	v_mul_f32_e32 v102, v102, v220
	v_mul_f32_e32 v103, v103, v221
	v_mul_f32_e32 v104, v104, v222
	v_mul_f32_e32 v105, v105, v223
	v_mul_f32_e32 v110, v110, v106
	v_mul_f32_e32 v111, v111, v107
	v_mul_f32_e32 v112, v112, v108
	v_mul_f32_e32 v113, v113, v109
	v_mul_f32_e32 v102, v102, v98
	v_mul_f32_e32 v103, v103, v99
	v_mul_f32_e32 v104, v104, v100
	v_mul_f32_e32 v105, v105, v101
	v_cvt_pk_bf16_f32 v110, v110, v111
	v_cvt_pk_bf16_f32 v111, v112, v113
	v_cvt_pk_bf16_f32 v102, v102, v103
	v_cvt_pk_bf16_f32 v103, v104, v105
	ds_write_b64 v228, v[110:111] offset:13056
	ds_write_b64 v228, v[102:103] offset:13088
	v_mul_f32_e32 v208, 0xbfb8aa3b, v94
	v_mul_f32_e32 v209, 0xbfb8aa3b, v95
	v_mul_f32_e32 v210, 0xbfb8aa3b, v96
	v_mul_f32_e32 v211, 0xbfb8aa3b, v97
	v_mul_f32_e32 v212, 0xbfb8aa3b, v86
	v_mul_f32_e32 v213, 0xbfb8aa3b, v87
	v_mul_f32_e32 v214, 0xbfb8aa3b, v88
	v_mul_f32_e32 v215, 0xbfb8aa3b, v89
	v_min_f32_e32 v208, 0x42fc0000, v208
	v_min_f32_e32 v209, 0x42fc0000, v209
	v_min_f32_e32 v210, 0x42fc0000, v210
	v_min_f32_e32 v211, 0x42fc0000, v211
	v_min_f32_e32 v212, 0x42fc0000, v212
	v_min_f32_e32 v213, 0x42fc0000, v213
	v_min_f32_e32 v214, 0x42fc0000, v214
	v_min_f32_e32 v215, 0x42fc0000, v215
	v_exp_f32_e32 v208, v208
	v_exp_f32_e32 v209, v209
	v_exp_f32_e32 v210, v210
	v_exp_f32_e32 v211, v211
	v_exp_f32_e32 v212, v212
	v_exp_f32_e32 v213, v213
	v_exp_f32_e32 v214, v214
	v_exp_f32_e32 v215, v215
	v_add_f32_e32 v208, 1.0, v208
	v_add_f32_e32 v209, 1.0, v209
	v_add_f32_e32 v210, 1.0, v210
	v_add_f32_e32 v211, 1.0, v211
	v_add_f32_e32 v212, 1.0, v212
	v_add_f32_e32 v213, 1.0, v213
	v_add_f32_e32 v214, 1.0, v214
	v_add_f32_e32 v215, 1.0, v215
	v_rcp_f32_e32 v216, v208
	v_rcp_f32_e32 v217, v209
	v_rcp_f32_e32 v218, v210
	v_rcp_f32_e32 v219, v211
	v_rcp_f32_e32 v220, v212
	v_rcp_f32_e32 v221, v213
	v_rcp_f32_e32 v222, v214
	v_rcp_f32_e32 v223, v215
	v_fma_f32 v208, -v208, v216, 1.0
	v_fma_f32 v209, -v209, v217, 1.0
	v_fma_f32 v210, -v210, v218, 1.0
	v_fma_f32 v211, -v211, v219, 1.0
	v_fma_f32 v212, -v212, v220, 1.0
	v_fma_f32 v213, -v213, v221, 1.0
	v_fma_f32 v214, -v214, v222, 1.0
	v_fma_f32 v215, -v215, v223, 1.0
	v_fmac_f32_e32 v216, v208, v216
	v_fmac_f32_e32 v217, v209, v217
	v_fmac_f32_e32 v218, v210, v218
	v_fmac_f32_e32 v219, v211, v219
	v_fmac_f32_e32 v220, v212, v220
	v_fmac_f32_e32 v221, v213, v221
	v_fmac_f32_e32 v222, v214, v222
	v_fmac_f32_e32 v223, v215, v223
	v_mul_f32_e32 v94, v94, v216
	v_mul_f32_e32 v95, v95, v217
	v_mul_f32_e32 v96, v96, v218
	v_mul_f32_e32 v97, v97, v219
	v_mul_f32_e32 v86, v86, v220
	v_mul_f32_e32 v87, v87, v221
	v_mul_f32_e32 v88, v88, v222
	v_mul_f32_e32 v89, v89, v223
	v_mul_f32_e32 v94, v94, v90
	v_mul_f32_e32 v95, v95, v91
	v_mul_f32_e32 v96, v96, v92
	v_mul_f32_e32 v97, v97, v93
	v_mul_f32_e32 v86, v86, v82
	v_mul_f32_e32 v87, v87, v83
	v_mul_f32_e32 v88, v88, v84
	v_mul_f32_e32 v89, v89, v85
	v_cvt_pk_bf16_f32 v94, v94, v95
	v_cvt_pk_bf16_f32 v95, v96, v97
	v_cvt_pk_bf16_f32 v86, v86, v87
	v_cvt_pk_bf16_f32 v87, v88, v89
	ds_write_b64 v228, v[94:95] offset:17408
	ds_write_b64 v228, v[86:87] offset:17440
	v_mul_f32_e32 v208, 0xbfb8aa3b, v78
	v_mul_f32_e32 v209, 0xbfb8aa3b, v79
	v_mul_f32_e32 v210, 0xbfb8aa3b, v80
	v_mul_f32_e32 v211, 0xbfb8aa3b, v81
	v_mul_f32_e32 v212, 0xbfb8aa3b, v70
	v_mul_f32_e32 v213, 0xbfb8aa3b, v71
	v_mul_f32_e32 v214, 0xbfb8aa3b, v72
	v_mul_f32_e32 v215, 0xbfb8aa3b, v73
	v_min_f32_e32 v208, 0x42fc0000, v208
	v_min_f32_e32 v209, 0x42fc0000, v209
	v_min_f32_e32 v210, 0x42fc0000, v210
	v_min_f32_e32 v211, 0x42fc0000, v211
	v_min_f32_e32 v212, 0x42fc0000, v212
	v_min_f32_e32 v213, 0x42fc0000, v213
	v_min_f32_e32 v214, 0x42fc0000, v214
	v_min_f32_e32 v215, 0x42fc0000, v215
	v_exp_f32_e32 v208, v208
	v_exp_f32_e32 v209, v209
	v_exp_f32_e32 v210, v210
	v_exp_f32_e32 v211, v211
	v_exp_f32_e32 v212, v212
	v_exp_f32_e32 v213, v213
	v_exp_f32_e32 v214, v214
	v_exp_f32_e32 v215, v215
	v_add_f32_e32 v208, 1.0, v208
	v_add_f32_e32 v209, 1.0, v209
	v_add_f32_e32 v210, 1.0, v210
	v_add_f32_e32 v211, 1.0, v211
	v_add_f32_e32 v212, 1.0, v212
	v_add_f32_e32 v213, 1.0, v213
	v_add_f32_e32 v214, 1.0, v214
	v_add_f32_e32 v215, 1.0, v215
	v_rcp_f32_e32 v216, v208
	v_rcp_f32_e32 v217, v209
	v_rcp_f32_e32 v218, v210
	v_rcp_f32_e32 v219, v211
	v_rcp_f32_e32 v220, v212
	v_rcp_f32_e32 v221, v213
	v_rcp_f32_e32 v222, v214
	v_rcp_f32_e32 v223, v215
	v_fma_f32 v208, -v208, v216, 1.0
	v_fma_f32 v209, -v209, v217, 1.0
	v_fma_f32 v210, -v210, v218, 1.0
	v_fma_f32 v211, -v211, v219, 1.0
	v_fma_f32 v212, -v212, v220, 1.0
	v_fma_f32 v213, -v213, v221, 1.0
	v_fma_f32 v214, -v214, v222, 1.0
	v_fma_f32 v215, -v215, v223, 1.0
	v_fmac_f32_e32 v216, v208, v216
	v_fmac_f32_e32 v217, v209, v217
	v_fmac_f32_e32 v218, v210, v218
	v_fmac_f32_e32 v219, v211, v219
	v_fmac_f32_e32 v220, v212, v220
	v_fmac_f32_e32 v221, v213, v221
	v_fmac_f32_e32 v222, v214, v222
	v_fmac_f32_e32 v223, v215, v223
	v_mul_f32_e32 v78, v78, v216
	v_mul_f32_e32 v79, v79, v217
	v_mul_f32_e32 v80, v80, v218
	v_mul_f32_e32 v81, v81, v219
	v_mul_f32_e32 v70, v70, v220
	v_mul_f32_e32 v71, v71, v221
	v_mul_f32_e32 v72, v72, v222
	v_mul_f32_e32 v73, v73, v223
	v_mul_f32_e32 v78, v78, v74
	v_mul_f32_e32 v79, v79, v75
; __device__ __forceinline__ float siluf_(float x) { return x / (1.0f + __expf(-x)); }
; __device__ __forceinline__ void phase_ffn_up(const Params& p, const u16* Wgu, u16* smem, volatile LAS unsigned* vb_) {
;     ...
; #pragma unroll
;     for (int i = 0; i < 8; ++i)
; #pragma unroll
;       for (int jp = 0; jp < 2; ++jp) {
; #pragma unroll
;         for (int r = 0; r < 4; ++r) {
;           const float g = acc[i][2 * jp][r], u = acc[i][2 * jp + 1][r];
;           smem[(wm * 128 + i * 16 + (lane >> 4) * 4 + r) * 136 + (wn * 2 + jp) * 16 + (lane & 15)] = f2bf(siluf_(g) * u);
;         }
;         __builtin_amdgcn_sched_barrier(0);
;       }
;     __syncthreads();
	v_mul_f32_e32 v80, v80, v76
	v_mul_f32_e32 v81, v81, v77
	v_mul_f32_e32 v70, v70, v66
	v_mul_f32_e32 v71, v71, v67
	v_mul_f32_e32 v72, v72, v68
	v_mul_f32_e32 v73, v73, v69
	v_cvt_pk_bf16_f32 v78, v78, v79
	v_cvt_pk_bf16_f32 v79, v80, v81
	v_cvt_pk_bf16_f32 v70, v70, v71
	v_cvt_pk_bf16_f32 v71, v72, v73
	ds_write_b64 v228, v[78:79] offset:21760
	ds_write_b64 v228, v[70:71] offset:21792
	v_mul_f32_e32 v208, 0xbfb8aa3b, v62
	v_mul_f32_e32 v209, 0xbfb8aa3b, v63
	v_mul_f32_e32 v210, 0xbfb8aa3b, v64
	v_mul_f32_e32 v211, 0xbfb8aa3b, v65
	v_mul_f32_e32 v212, 0xbfb8aa3b, v54
	v_mul_f32_e32 v213, 0xbfb8aa3b, v55
	v_mul_f32_e32 v214, 0xbfb8aa3b, v56
	v_mul_f32_e32 v215, 0xbfb8aa3b, v57
	v_min_f32_e32 v208, 0x42fc0000, v208
	v_min_f32_e32 v209, 0x42fc0000, v209
	v_min_f32_e32 v210, 0x42fc0000, v210
	v_min_f32_e32 v211, 0x42fc0000, v211
	v_min_f32_e32 v212, 0x42fc0000, v212
	v_min_f32_e32 v213, 0x42fc0000, v213
	v_min_f32_e32 v214, 0x42fc0000, v214
	v_min_f32_e32 v215, 0x42fc0000, v215
	v_exp_f32_e32 v208, v208
	v_exp_f32_e32 v209, v209
	v_exp_f32_e32 v210, v210
	v_exp_f32_e32 v211, v211
	v_exp_f32_e32 v212, v212
	v_exp_f32_e32 v213, v213
	v_exp_f32_e32 v214, v214
	v_exp_f32_e32 v215, v215
	v_add_f32_e32 v208, 1.0, v208
	v_add_f32_e32 v209, 1.0, v209
	v_add_f32_e32 v210, 1.0, v210
	v_add_f32_e32 v211, 1.0, v211
	v_add_f32_e32 v212, 1.0, v212
	v_add_f32_e32 v213, 1.0, v213
	v_add_f32_e32 v214, 1.0, v214
	v_add_f32_e32 v215, 1.0, v215
	v_rcp_f32_e32 v216, v208
	v_rcp_f32_e32 v217, v209
	v_rcp_f32_e32 v218, v210
	v_rcp_f32_e32 v219, v211
	v_rcp_f32_e32 v220, v212
	v_rcp_f32_e32 v221, v213
	v_rcp_f32_e32 v222, v214
	v_rcp_f32_e32 v223, v215
	v_fma_f32 v208, -v208, v216, 1.0
	v_fma_f32 v209, -v209, v217, 1.0
	v_fma_f32 v210, -v210, v218, 1.0
	v_fma_f32 v211, -v211, v219, 1.0
	v_fma_f32 v212, -v212, v220, 1.0
	v_fma_f32 v213, -v213, v221, 1.0
	v_fma_f32 v214, -v214, v222, 1.0
	v_fma_f32 v215, -v215, v223, 1.0
	v_fmac_f32_e32 v216, v208, v216
	v_fmac_f32_e32 v217, v209, v217
	v_fmac_f32_e32 v218, v210, v218
	v_fmac_f32_e32 v219, v211, v219
	v_fmac_f32_e32 v220, v212, v220
	v_fmac_f32_e32 v221, v213, v221
	v_fmac_f32_e32 v222, v214, v222
	v_fmac_f32_e32 v223, v215, v223
	v_mul_f32_e32 v62, v62, v216
	v_mul_f32_e32 v63, v63, v217
	v_mul_f32_e32 v64, v64, v218
	v_mul_f32_e32 v65, v65, v219
	v_mul_f32_e32 v54, v54, v220
	v_mul_f32_e32 v55, v55, v221
	v_mul_f32_e32 v56, v56, v222
	v_mul_f32_e32 v57, v57, v223
	v_mul_f32_e32 v62, v62, v58
	v_mul_f32_e32 v63, v63, v59
	v_mul_f32_e32 v64, v64, v60
	v_mul_f32_e32 v65, v65, v61
	v_mul_f32_e32 v54, v54, v50
	v_mul_f32_e32 v55, v55, v51
	v_mul_f32_e32 v56, v56, v52
	v_mul_f32_e32 v57, v57, v53
	v_cvt_pk_bf16_f32 v62, v62, v63
	v_cvt_pk_bf16_f32 v63, v64, v65
	v_cvt_pk_bf16_f32 v54, v54, v55
	v_cvt_pk_bf16_f32 v55, v56, v57
	ds_write_b64 v228, v[62:63] offset:26112
	ds_write_b64 v228, v[54:55] offset:26144
	v_mul_f32_e32 v208, 0xbfb8aa3b, v46
	v_mul_f32_e32 v209, 0xbfb8aa3b, v47
	v_mul_f32_e32 v210, 0xbfb8aa3b, v48
	v_mul_f32_e32 v211, 0xbfb8aa3b, v49
	v_mul_f32_e32 v212, 0xbfb8aa3b, v38
	v_mul_f32_e32 v213, 0xbfb8aa3b, v39
	v_mul_f32_e32 v214, 0xbfb8aa3b, v40
	v_mul_f32_e32 v215, 0xbfb8aa3b, v41
	v_min_f32_e32 v208, 0x42fc0000, v208
	v_min_f32_e32 v209, 0x42fc0000, v209
	v_min_f32_e32 v210, 0x42fc0000, v210
	v_min_f32_e32 v211, 0x42fc0000, v211
	v_min_f32_e32 v212, 0x42fc0000, v212
	v_min_f32_e32 v213, 0x42fc0000, v213
	v_min_f32_e32 v214, 0x42fc0000, v214
	v_min_f32_e32 v215, 0x42fc0000, v215
	v_exp_f32_e32 v208, v208
	v_exp_f32_e32 v209, v209
	v_exp_f32_e32 v210, v210
	v_exp_f32_e32 v211, v211
	v_exp_f32_e32 v212, v212
	v_exp_f32_e32 v213, v213
	v_exp_f32_e32 v214, v214
	v_exp_f32_e32 v215, v215
	v_add_f32_e32 v208, 1.0, v208
	v_add_f32_e32 v209, 1.0, v209
	v_add_f32_e32 v210, 1.0, v210
	v_add_f32_e32 v211, 1.0, v211
	v_add_f32_e32 v212, 1.0, v212
	v_add_f32_e32 v213, 1.0, v213
	v_add_f32_e32 v214, 1.0, v214
	v_add_f32_e32 v215, 1.0, v215
	v_rcp_f32_e32 v216, v208
	v_rcp_f32_e32 v217, v209
	v_rcp_f32_e32 v218, v210
	v_rcp_f32_e32 v219, v211
	v_rcp_f32_e32 v220, v212
	v_rcp_f32_e32 v221, v213
	v_rcp_f32_e32 v222, v214
	v_rcp_f32_e32 v223, v215
	v_fma_f32 v208, -v208, v216, 1.0
	v_fma_f32 v209, -v209, v217, 1.0
	v_fma_f32 v210, -v210, v218, 1.0
	v_fma_f32 v211, -v211, v219, 1.0
	v_fma_f32 v212, -v212, v220, 1.0
	v_fma_f32 v213, -v213, v221, 1.0
	v_fma_f32 v214, -v214, v222, 1.0
	v_fma_f32 v215, -v215, v223, 1.0
	v_fmac_f32_e32 v216, v208, v216
	v_fmac_f32_e32 v217, v209, v217
	v_fmac_f32_e32 v218, v210, v218
	v_fmac_f32_e32 v219, v211, v219
	v_fmac_f32_e32 v220, v212, v220
	v_fmac_f32_e32 v221, v213, v221
	v_fmac_f32_e32 v222, v214, v222
	v_fmac_f32_e32 v223, v215, v223
	v_mul_f32_e32 v46, v46, v216
	v_mul_f32_e32 v47, v47, v217
	v_mul_f32_e32 v48, v48, v218
	v_mul_f32_e32 v49, v49, v219
	v_mul_f32_e32 v38, v38, v220
	v_mul_f32_e32 v39, v39, v221
	v_mul_f32_e32 v40, v40, v222
	v_mul_f32_e32 v41, v41, v223
	v_mul_f32_e32 v46, v46, v42
	v_mul_f32_e32 v47, v47, v43
	v_mul_f32_e32 v48, v48, v44
	v_mul_f32_e32 v49, v49, v45
	v_mul_f32_e32 v38, v38, v34
	v_mul_f32_e32 v39, v39, v35
	v_mul_f32_e32 v40, v40, v36
	v_mul_f32_e32 v41, v41, v37
	v_cvt_pk_bf16_f32 v46, v46, v47
	v_cvt_pk_bf16_f32 v47, v48, v49
	v_cvt_pk_bf16_f32 v38, v38, v39
	v_cvt_pk_bf16_f32 v39, v40, v41
	ds_write_b64 v228, v[46:47] offset:30464
	ds_write_b64 v228, v[38:39] offset:30496
	s_waitcnt lgkmcnt(0)
	s_barrier
; __device__ __forceinline__ void phase_ffn_up(const Params& p, const u16* Wgu, u16* smem, volatile LAS unsigned* vb_) {
;     ...
; #pragma unroll
;     for (int k = 0; k < 8; ++k) {
;       const int c = tid + 512 * k;
;       const int row = c >> 4, ch = c & 15;
;       const uint4 v = *(const uint4*)(smem + row * 136 + ch * 8);
;       *(uint4*)(act + (size_t)(mt * 256 + row) * DFF + nt * 128 + ch * 8) = v;
;     }
;     __syncthreads();
	s_lshl_b32 s12, s40, 7
	s_ashr_i32 s13, s12, 31
	v_lshl_add_u64 v[38:39], s[12:13], 1, v[166:167]
	s_and_b64 vcc, exec, s[10:11]
	s_mov_b32 s20, s41
	ds_read_b128 v[34:37], v197
	s_add_i32 s49, s39, 0
	v_add_u32_e32 v40, s49, v189
	v_mad_i64_i32 v[40:41], s[12:13], v40, s7, v[38:39]
	s_waitcnt lgkmcnt(0)
	global_store_dwordx4 v[40:41], v[34:37], off
	ds_read_b128 v[34:37], v197 offset:8704
	s_add_i32 s49, s39, 32
	v_add_u32_e32 v40, s49, v189
	v_mad_i64_i32 v[40:41], s[12:13], v40, s7, v[38:39]
	s_waitcnt lgkmcnt(0)
	global_store_dwordx4 v[40:41], v[34:37], off
	ds_read_b128 v[34:37], v197 offset:17408
	s_add_i32 s49, s39, 64
	v_add_u32_e32 v40, s49, v189
	v_mad_i64_i32 v[40:41], s[12:13], v40, s7, v[38:39]
	s_waitcnt lgkmcnt(0)
	global_store_dwordx4 v[40:41], v[34:37], off
	ds_read_b128 v[34:37], v197 offset:26112
	s_add_i32 s49, s39, 96
	v_add_u32_e32 v40, s49, v189
	v_mad_i64_i32 v[40:41], s[12:13], v40, s7, v[38:39]
	s_waitcnt lgkmcnt(0)
	global_store_dwordx4 v[40:41], v[34:37], off
	ds_read_b128 v[34:37], v197 offset:34816
	s_add_i32 s49, s39, 128
	v_add_u32_e32 v40, s49, v189
	v_mad_i64_i32 v[40:41], s[12:13], v40, s7, v[38:39]
	s_waitcnt lgkmcnt(0)
	global_store_dwordx4 v[40:41], v[34:37], off
	ds_read_b128 v[34:37], v197 offset:43520
	s_add_i32 s49, s39, 160
	v_add_u32_e32 v40, s49, v189
	v_mad_i64_i32 v[40:41], s[12:13], v40, s7, v[38:39]
	s_waitcnt lgkmcnt(0)
	global_store_dwordx4 v[40:41], v[34:37], off
	ds_read_b128 v[34:37], v197 offset:52224
	s_add_i32 s49, s39, 192
	v_add_u32_e32 v40, s49, v189
	v_mad_i64_i32 v[40:41], s[12:13], v40, s7, v[38:39]
	s_waitcnt lgkmcnt(0)
	global_store_dwordx4 v[40:41], v[34:37], off
	ds_read_b128 v[34:37], v197 offset:60928
	s_add_i32 s49, s39, 224
	v_add_u32_e32 v40, s49, v189
	v_mad_i64_i32 v[40:41], s[12:13], v40, s7, v[38:39]
	s_waitcnt lgkmcnt(0)
	global_store_dwordx4 v[40:41], v[34:37], off
	s_mov_b64 s[12:13], -1
	s_barrier
	s_cbranch_vccz .LBB0_598
